# GEMM epilogue dwordx4 stores made write-through (sc1) so the grid barrier's L2 write-back has less to flush
# baseline (speedup 1.0000x reference)
.LBB0_165:
	v_lshl_or_b32 v174, s64, 8, v190
	v_lshl_add_u32 v186, s62, 8, v188
	v_ashrrev_i32_e32 v175, 31, v174
	v_readlane_b32 s0, v254, 43
	v_lshlrev_b64 v[200:201], 1, v[174:175]
	v_readlane_b32 s1, v254, 44
	v_ashrrev_i32_e32 v187, 31, v186
	v_lshlrev_b64 v[178:179], 11, v[186:187]
	v_lshl_add_u64 v[176:177], s[0:1], 0, v[200:201]
	v_lshl_add_u64 v[114:115], v[176:177], 0, v[178:179]
	global_load_dwordx4 v[192:195], v[114:115], off
	global_load_dwordx4 v[196:199], v[114:115], off offset:256
	v_or_b32_e32 v114, 16, v186
	v_ashrrev_i32_e32 v115, 31, v114
	v_lshlrev_b64 v[184:185], 11, v[114:115]
	v_lshl_add_u64 v[114:115], v[176:177], 0, v[184:185]
	global_load_dwordx4 v[134:137], v[114:115], off
	global_load_dwordx4 v[130:133], v[114:115], off offset:256
	v_or_b32_e32 v114, 32, v186
	v_ashrrev_i32_e32 v115, 31, v114
	v_lshlrev_b64 v[182:183], 11, v[114:115]
	v_lshl_add_u64 v[114:115], v[176:177], 0, v[182:183]
	global_load_dwordx4 v[126:129], v[114:115], off
	global_load_dwordx4 v[122:125], v[114:115], off offset:256
	v_or_b32_e32 v114, 48, v186
	v_ashrrev_i32_e32 v115, 31, v114
	v_lshlrev_b64 v[180:181], 11, v[114:115]
	v_lshl_add_u64 v[114:115], v[176:177], 0, v[180:181]
	global_load_dwordx4 v[118:121], v[114:115], off
	s_nop 0
	global_load_dwordx4 v[114:117], v[114:115], off offset:256
	s_waitcnt vmcnt(0)
	v_lshlrev_b32_e32 v202, 16, v192
	v_add_f32_e32 v202, v150, v202
	v_and_b32_e32 v150, 0xffff0000, v192
	v_add_f32_e32 v192, v151, v150
	v_lshlrev_b32_e32 v150, 16, v193
	v_add_f32_e32 v152, v152, v150
	v_and_b32_e32 v150, 0xffff0000, v193
	v_add_f32_e32 v153, v153, v150
	v_lshlrev_b32_e32 v150, 16, v194
	v_add_f32_e32 v193, v146, v150
	v_and_b32_e32 v146, 0xffff0000, v194
	v_add_f32_e32 v194, v147, v146
	v_lshlrev_b32_e32 v146, 16, v195
	v_add_f32_e32 v203, v148, v146
	v_and_b32_e32 v146, 0xffff0000, v195
	v_lshl_add_u64 v[150:151], s[0:1], 0, v[178:179]
	v_add_f32_e32 v195, v149, v146
	v_cvt_pk_bf16_f32 v146, v202, v192
	v_cvt_pk_bf16_f32 v147, v152, v153
	v_lshl_add_u64 v[150:151], v[150:151], 0, v[200:201]
	v_cvt_pk_bf16_f32 v148, v193, v194
	v_cvt_pk_bf16_f32 v149, v203, v195
	global_store_dwordx4 v[150:151], v[146:149], off sc1
	s_nop 1
	v_mul_f32_e32 v146, v192, v192
	v_mul_f32_e32 v147, v153, v153
	v_fmac_f32_e32 v146, v202, v202
	v_fmac_f32_e32 v147, v152, v152
	v_add_f32_e32 v146, v146, v147
	v_mul_f32_e32 v147, v194, v194
	v_fmac_f32_e32 v147, v193, v193
	v_add_f32_e32 v146, v147, v146
	v_mul_f32_e32 v147, v195, v195
	v_fmac_f32_e32 v147, v203, v203
	v_add_f32_e32 v146, v147, v146
	v_lshlrev_b32_e32 v147, 16, v196
	v_add_f32_e32 v142, v142, v147
	v_and_b32_e32 v147, 0xffff0000, v196
	v_add_f32_e32 v143, v143, v147
	v_lshlrev_b32_e32 v147, 16, v197
	v_add_f32_e32 v144, v144, v147
	v_and_b32_e32 v147, 0xffff0000, v197
	v_add_f32_e32 v145, v145, v147
	v_lshlrev_b32_e32 v147, 16, v198
	v_add_f32_e32 v147, v138, v147
	v_and_b32_e32 v138, 0xffff0000, v198
	v_add_f32_e32 v148, v139, v138
	v_lshlrev_b32_e32 v138, 16, v199
	v_add_f32_e32 v149, v140, v138
	v_and_b32_e32 v138, 0xffff0000, v199
	v_add_f32_e32 v152, v141, v138
	v_cvt_pk_bf16_f32 v138, v142, v143
	v_cvt_pk_bf16_f32 v139, v144, v145
	v_cvt_pk_bf16_f32 v140, v147, v148
	v_cvt_pk_bf16_f32 v141, v149, v152
	global_store_dwordx4 v[150:151], v[138:141], off offset:256 sc1
	s_nop 1
	v_mul_f32_e32 v138, v143, v143
	v_mul_f32_e32 v139, v145, v145
	v_fmac_f32_e32 v138, v142, v142
	v_fmac_f32_e32 v139, v144, v144
	v_add_f32_e32 v138, v138, v139
	v_mul_f32_e32 v139, v148, v148
	v_fmac_f32_e32 v139, v147, v147
	v_add_f32_e32 v138, v139, v138
	v_mul_f32_e32 v139, v152, v152
	v_fmac_f32_e32 v139, v149, v149
	v_and_b32_e32 v140, 64, v211
	v_add_f32_e32 v138, v139, v138
	v_xor_b32_e32 v139, 16, v211
	v_add_u32_e32 v141, 64, v140
	v_cmp_lt_i32_e32 vcc, v139, v141
	v_add_f32_e32 v138, v146, v138
	s_nop 0
	v_cndmask_b32_e32 v139, v211, v139, vcc
	v_lshlrev_b32_e32 v140, 2, v139
	ds_bpermute_b32 v139, v140, v138
	s_waitcnt lgkmcnt(0)
	v_add_f32_e32 v142, v138, v139
	v_xor_b32_e32 v138, 32, v211
	v_cmp_lt_i32_e32 vcc, v138, v141
	s_nop 1
	v_cndmask_b32_e32 v138, v211, v138, vcc
	v_lshlrev_b32_e32 v141, 2, v138
	ds_bpermute_b32 v143, v141, v142
	v_lshl_add_u64 v[138:139], v[186:187], 3, s[36:37]
	s_and_saveexec_b64 s[0:1], s[40:41]
	v_readlane_b32 s66, v254, 47
	v_readlane_b32 s67, v254, 48
	s_load_dwordx2 s[78:79], s[66:67], 0x98
	s_movk_i32 s22, 0x5800
	s_mov_b32 s23, 0xb000
	s_mov_b32 s24, 0x3f317217
	s_cbranch_execz .LBB0_167
	s_waitcnt lgkmcnt(0)
	v_add_f32_e32 v142, v142, v143
	v_mul_f32_e32 v142, 0x4b800000, v142
	v_rndne_f32_e32 v142, v142
	v_mul_f32_e32 v143, 0x2f800000, v142
	v_floor_f32_e32 v143, v143
	v_fmac_f32_e32 v142, 0xcf800000, v143
	v_cvt_u32_f32_e32 v142, v142
	v_cvt_u32_f32_e32 v143, v143
	global_atomic_add_x2 v[138:139], v[142:143], off
.LBB0_167:
	s_or_b64 exec, exec, s[0:1]
	v_lshlrev_b32_e32 v142, 16, v134
	v_and_b32_e32 v134, 0xffff0000, v134
	v_add_f32_e32 v111, v111, v134
	v_lshlrev_b32_e32 v134, 16, v135
	v_add_f32_e32 v112, v112, v134
	v_and_b32_e32 v134, 0xffff0000, v135
	v_add_f32_e32 v113, v113, v134
	v_lshlrev_b32_e32 v134, 16, v136
	v_add_f32_e32 v134, v106, v134
	v_and_b32_e32 v106, 0xffff0000, v136
	v_add_f32_e32 v135, v107, v106
	v_lshlrev_b32_e32 v106, 16, v137
	v_add_f32_e32 v136, v108, v106
	v_and_b32_e32 v106, 0xffff0000, v137
	v_add_f32_e32 v110, v110, v142
	v_add_f32_e32 v137, v109, v106
	v_cvt_pk_bf16_f32 v106, v110, v111
	v_mul_f32_e32 v111, v111, v111
	v_fmac_f32_e32 v111, v110, v110
	v_mul_f32_e32 v110, v113, v113
	v_fmac_f32_e32 v110, v112, v112
	v_add_f32_e32 v110, v111, v110
	v_mul_f32_e32 v111, v135, v135
	v_fmac_f32_e32 v111, v134, v134
	v_add_f32_e32 v110, v111, v110
	v_mul_f32_e32 v111, v137, v137
	v_fmac_f32_e32 v111, v136, v136
	v_add_f32_e32 v110, v111, v110
	v_lshlrev_b32_e32 v111, 16, v130
	v_add_f32_e32 v102, v102, v111
	v_and_b32_e32 v111, 0xffff0000, v130
	v_add_f32_e32 v103, v103, v111
	v_lshlrev_b32_e32 v111, 16, v131
	v_add_f32_e32 v111, v104, v111
	v_and_b32_e32 v104, 0xffff0000, v131
	v_cvt_pk_bf16_f32 v107, v112, v113
	v_add_f32_e32 v112, v105, v104
	v_lshlrev_b32_e32 v104, 16, v132
	v_add_f32_e32 v113, v98, v104
	v_and_b32_e32 v98, 0xffff0000, v132
	v_add_f32_e32 v130, v99, v98
	v_lshlrev_b32_e32 v98, 16, v133
	v_add_f32_e32 v131, v100, v98
	v_and_b32_e32 v98, 0xffff0000, v133
	v_add_f32_e32 v132, v101, v98
	v_mul_f32_e32 v98, v103, v103
	v_mul_f32_e32 v99, v112, v112
	v_fmac_f32_e32 v98, v102, v102
	v_fmac_f32_e32 v99, v111, v111
	v_add_f32_e32 v98, v98, v99
	v_mul_f32_e32 v99, v130, v130
	v_fmac_f32_e32 v99, v113, v113
	v_add_f32_e32 v98, v99, v98
	v_mul_f32_e32 v99, v132, v132
	v_fmac_f32_e32 v99, v131, v131
	v_add_f32_e32 v98, v99, v98
	v_add_f32_e32 v101, v110, v98
	ds_bpermute_b32 v110, v140, v101
	v_readlane_b32 s0, v254, 43
	v_readlane_b32 s1, v254, 44
	v_cvt_pk_bf16_f32 v108, v134, v135
	v_cvt_pk_bf16_f32 v109, v136, v137
	v_cvt_pk_bf16_f32 v100, v102, v103
	v_cvt_pk_bf16_f32 v102, v113, v130
	v_cvt_pk_bf16_f32 v103, v131, v132
	s_nop 1
	v_lshl_add_u64 v[98:99], s[0:1], 0, v[184:185]
	v_lshl_add_u64 v[104:105], v[174:175], 1, v[98:99]
	s_waitcnt lgkmcnt(0)
	v_add_f32_e32 v98, v101, v110
	ds_bpermute_b32 v99, v141, v98
	global_store_dwordx4 v[104:105], v[106:109], off sc1
	v_cvt_pk_bf16_f32 v101, v111, v112
	global_store_dwordx4 v[104:105], v[100:103], off offset:256 sc1
	s_and_saveexec_b64 s[0:1], s[40:41]
	s_cbranch_execz .LBB0_169
	s_waitcnt lgkmcnt(0)
	v_add_f32_e32 v98, v98, v99
	v_mul_f32_e32 v98, 0x4b800000, v98
	v_rndne_f32_e32 v98, v98
	v_mul_f32_e32 v99, 0x2f800000, v98
	v_floor_f32_e32 v99, v99
	v_fmac_f32_e32 v98, 0xcf800000, v99
	v_cvt_u32_f32_e32 v98, v98
	v_cvt_u32_f32_e32 v99, v99
	global_atomic_add_x2 v[138:139], v[98:99], off offset:128
.LBB0_169:
	s_or_b64 exec, exec, s[0:1]
	v_lshlrev_b32_e32 v98, 16, v126
	v_add_f32_e32 v94, v94, v98
	v_and_b32_e32 v98, 0xffff0000, v126
	v_add_f32_e32 v95, v95, v98
	v_lshlrev_b32_e32 v98, 16, v127
	v_add_f32_e32 v96, v96, v98
	v_and_b32_e32 v98, 0xffff0000, v127
	v_add_f32_e32 v97, v97, v98
	v_lshlrev_b32_e32 v98, 16, v128
	v_add_f32_e32 v98, v90, v98
	v_and_b32_e32 v90, 0xffff0000, v128
	s_waitcnt lgkmcnt(0)
	v_add_f32_e32 v99, v91, v90
	v_lshlrev_b32_e32 v90, 16, v129
	v_add_f32_e32 v100, v92, v90
	v_and_b32_e32 v90, 0xffff0000, v129
	v_add_f32_e32 v101, v93, v90
	v_cvt_pk_bf16_f32 v90, v94, v95
	v_mul_f32_e32 v95, v95, v95
	v_fmac_f32_e32 v95, v94, v94
	v_mul_f32_e32 v94, v97, v97
	v_fmac_f32_e32 v94, v96, v96
	v_add_f32_e32 v94, v95, v94
	v_mul_f32_e32 v95, v99, v99
	v_fmac_f32_e32 v95, v98, v98
	v_add_f32_e32 v94, v95, v94
	v_mul_f32_e32 v95, v101, v101
	v_fmac_f32_e32 v95, v100, v100
	v_add_f32_e32 v94, v95, v94
	v_lshlrev_b32_e32 v95, 16, v122
	v_add_f32_e32 v86, v86, v95
	v_and_b32_e32 v95, 0xffff0000, v122
	v_add_f32_e32 v87, v87, v95
	v_lshlrev_b32_e32 v95, 16, v123
	v_add_f32_e32 v95, v88, v95
	v_and_b32_e32 v88, 0xffff0000, v123
	v_cvt_pk_bf16_f32 v91, v96, v97
	v_add_f32_e32 v96, v89, v88
	v_lshlrev_b32_e32 v88, 16, v124
	v_add_f32_e32 v97, v82, v88
	v_and_b32_e32 v82, 0xffff0000, v124
	v_cvt_pk_bf16_f32 v92, v98, v99
	v_add_f32_e32 v98, v83, v82
	v_lshlrev_b32_e32 v82, 16, v125
	v_add_f32_e32 v99, v84, v82
	v_and_b32_e32 v82, 0xffff0000, v125
	v_cvt_pk_bf16_f32 v93, v100, v101
	v_add_f32_e32 v100, v85, v82
	v_mul_f32_e32 v82, v87, v87
	v_mul_f32_e32 v83, v96, v96
	v_fmac_f32_e32 v82, v86, v86
	v_fmac_f32_e32 v83, v95, v95
	v_add_f32_e32 v82, v82, v83
	v_mul_f32_e32 v83, v98, v98
	v_fmac_f32_e32 v83, v97, v97
	v_add_f32_e32 v82, v83, v82
	v_mul_f32_e32 v83, v100, v100
	v_fmac_f32_e32 v83, v99, v99
	v_add_f32_e32 v82, v83, v82
	v_add_f32_e32 v85, v94, v82
	ds_bpermute_b32 v94, v140, v85
	v_readlane_b32 s0, v254, 43
	v_readlane_b32 s1, v254, 44
	v_cvt_pk_bf16_f32 v84, v86, v87
	v_cvt_pk_bf16_f32 v86, v97, v98
	v_cvt_pk_bf16_f32 v87, v99, v100
	s_nop 1
	v_lshl_add_u64 v[82:83], s[0:1], 0, v[182:183]
	v_lshl_add_u64 v[88:89], v[174:175], 1, v[82:83]
	s_waitcnt lgkmcnt(0)
	v_add_f32_e32 v82, v85, v94
	ds_bpermute_b32 v83, v141, v82
	global_store_dwordx4 v[88:89], v[90:93], off sc1
	v_cvt_pk_bf16_f32 v85, v95, v96
	global_store_dwordx4 v[88:89], v[84:87], off offset:256 sc1
	s_and_saveexec_b64 s[0:1], s[40:41]
	v_readlane_b32 s34, v254, 40
	s_cbranch_execz .LBB0_171
	s_waitcnt lgkmcnt(0)
	v_add_f32_e32 v82, v82, v83
	v_mul_f32_e32 v82, 0x4b800000, v82
	v_rndne_f32_e32 v82, v82
	v_mul_f32_e32 v83, 0x2f800000, v82
	v_floor_f32_e32 v83, v83
	v_fmac_f32_e32 v82, 0xcf800000, v83
	v_cvt_u32_f32_e32 v82, v82
	v_cvt_u32_f32_e32 v83, v83
	global_atomic_add_x2 v[138:139], v[82:83], off offset:256
.LBB0_171:
	s_or_b64 exec, exec, s[0:1]
	v_lshlrev_b32_e32 v82, 16, v118
	v_add_f32_e32 v78, v78, v82
	v_and_b32_e32 v82, 0xffff0000, v118
	v_add_f32_e32 v79, v79, v82
	v_lshlrev_b32_e32 v82, 16, v119
	v_add_f32_e32 v80, v80, v82
	v_and_b32_e32 v82, 0xffff0000, v119
	v_add_f32_e32 v81, v81, v82
	v_lshlrev_b32_e32 v82, 16, v120
	v_add_f32_e32 v82, v74, v82
	v_and_b32_e32 v74, 0xffff0000, v120
	s_waitcnt lgkmcnt(0)
	v_add_f32_e32 v83, v75, v74
	v_lshlrev_b32_e32 v74, 16, v121
	v_add_f32_e32 v84, v76, v74
	v_and_b32_e32 v74, 0xffff0000, v121
	v_add_f32_e32 v85, v77, v74
	v_cvt_pk_bf16_f32 v74, v78, v79
	v_mul_f32_e32 v79, v79, v79
	v_fmac_f32_e32 v79, v78, v78
	v_mul_f32_e32 v78, v81, v81
	v_fmac_f32_e32 v78, v80, v80
	v_add_f32_e32 v78, v79, v78
	v_mul_f32_e32 v79, v83, v83
	v_fmac_f32_e32 v79, v82, v82
	v_add_f32_e32 v78, v79, v78
	v_mul_f32_e32 v79, v85, v85
	v_fmac_f32_e32 v79, v84, v84
	v_add_f32_e32 v78, v79, v78
	v_lshlrev_b32_e32 v79, 16, v114
	v_add_f32_e32 v70, v70, v79
	v_and_b32_e32 v79, 0xffff0000, v114
	v_add_f32_e32 v71, v71, v79
	v_lshlrev_b32_e32 v79, 16, v115
	v_add_f32_e32 v79, v72, v79
	v_and_b32_e32 v72, 0xffff0000, v115
	v_cvt_pk_bf16_f32 v75, v80, v81
	v_add_f32_e32 v80, v73, v72
	v_lshlrev_b32_e32 v72, 16, v116
	v_add_f32_e32 v81, v66, v72
	v_and_b32_e32 v66, 0xffff0000, v116
	v_cvt_pk_bf16_f32 v76, v82, v83
	v_add_f32_e32 v82, v67, v66
	v_lshlrev_b32_e32 v66, 16, v117
	v_add_f32_e32 v83, v68, v66
	v_and_b32_e32 v66, 0xffff0000, v117
	v_cvt_pk_bf16_f32 v77, v84, v85
	v_add_f32_e32 v84, v69, v66
	v_mul_f32_e32 v66, v71, v71
	v_mul_f32_e32 v67, v80, v80
	v_fmac_f32_e32 v66, v70, v70
	v_fmac_f32_e32 v67, v79, v79
	v_add_f32_e32 v66, v66, v67
	v_mul_f32_e32 v67, v82, v82
	v_fmac_f32_e32 v67, v81, v81
	v_add_f32_e32 v66, v67, v66
	v_mul_f32_e32 v67, v84, v84
	v_fmac_f32_e32 v67, v83, v83
	v_add_f32_e32 v66, v67, v66
	v_add_f32_e32 v69, v78, v66
	ds_bpermute_b32 v78, v140, v69
	v_readlane_b32 s0, v254, 43
	v_readlane_b32 s1, v254, 44
	v_cvt_pk_bf16_f32 v68, v70, v71
	v_cvt_pk_bf16_f32 v70, v81, v82
	v_cvt_pk_bf16_f32 v71, v83, v84
	s_nop 1
	v_lshl_add_u64 v[66:67], s[0:1], 0, v[180:181]
	v_lshl_add_u64 v[72:73], v[174:175], 1, v[66:67]
	s_waitcnt lgkmcnt(0)
	v_add_f32_e32 v66, v69, v78
	ds_bpermute_b32 v67, v141, v66
	global_store_dwordx4 v[72:73], v[74:77], off sc1
	v_cvt_pk_bf16_f32 v69, v79, v80
	global_store_dwordx4 v[72:73], v[68:71], off offset:256 sc1
	s_and_saveexec_b64 s[0:1], s[40:41]
	s_cbranch_execz .LBB0_173
	s_waitcnt lgkmcnt(0)
	v_add_f32_e32 v66, v66, v67
	v_mul_f32_e32 v66, 0x4b800000, v66
	v_rndne_f32_e32 v66, v66
	v_mul_f32_e32 v67, 0x2f800000, v66
	v_floor_f32_e32 v67, v67
	v_fmac_f32_e32 v66, 0xcf800000, v67
	v_cvt_u32_f32_e32 v66, v66
	v_cvt_u32_f32_e32 v67, v67
	global_atomic_add_x2 v[138:139], v[66:67], off offset:384
.LBB0_173:
	s_or_b64 exec, exec, s[0:1]
	s_mov_b64 s[0:1], 0x40000
	v_lshl_add_u64 v[104:105], v[178:179], 0, s[0:1]
	s_waitcnt lgkmcnt(0)
	v_lshl_add_u64 v[66:67], v[176:177], 0, v[104:105]
	global_load_dwordx4 v[100:103], v[66:67], off
	global_load_dwordx4 v[90:93], v[66:67], off offset:256
	s_mov_b64 s[0:1], 0x48000
	v_lshl_add_u64 v[98:99], v[178:179], 0, s[0:1]
	s_mov_b64 s[0:1], 0x50000
	v_lshl_add_u64 v[66:67], v[176:177], 0, v[98:99]
	v_lshl_add_u64 v[96:97], v[178:179], 0, s[0:1]
	s_mov_b64 s[0:1], 0x58000
	global_load_dwordx4 v[86:89], v[66:67], off
	global_load_dwordx4 v[82:85], v[66:67], off offset:256
	v_lshl_add_u64 v[66:67], v[176:177], 0, v[96:97]
	v_lshl_add_u64 v[94:95], v[178:179], 0, s[0:1]
	global_load_dwordx4 v[78:81], v[66:67], off
	global_load_dwordx4 v[74:77], v[66:67], off offset:256
	v_lshl_add_u64 v[66:67], v[176:177], 0, v[94:95]
	global_load_dwordx4 v[70:73], v[66:67], off
	s_nop 0
	global_load_dwordx4 v[66:69], v[66:67], off offset:256
	v_readlane_b32 s0, v254, 43
	v_readlane_b32 s1, v254, 44
	s_waitcnt vmcnt(7)
	v_lshlrev_b32_e32 v106, 16, v100
	v_add_f32_e32 v106, v62, v106
	v_and_b32_e32 v62, 0xffff0000, v100
	v_add_f32_e32 v100, v63, v62
	v_lshlrev_b32_e32 v62, 16, v101
	v_add_f32_e32 v64, v64, v62
	v_and_b32_e32 v62, 0xffff0000, v101
	v_add_f32_e32 v65, v65, v62
	v_lshlrev_b32_e32 v62, 16, v102
	v_add_f32_e32 v101, v58, v62
	v_and_b32_e32 v58, 0xffff0000, v102
	v_add_f32_e32 v102, v59, v58
	v_lshlrev_b32_e32 v58, 16, v103
	v_add_f32_e32 v107, v60, v58
	v_and_b32_e32 v58, 0xffff0000, v103
	v_lshl_add_u64 v[62:63], s[0:1], 0, v[104:105]
	v_add_f32_e32 v103, v61, v58
	v_cvt_pk_bf16_f32 v58, v106, v100
	v_cvt_pk_bf16_f32 v59, v64, v65
	v_lshl_add_u64 v[62:63], v[174:175], 1, v[62:63]
	v_cvt_pk_bf16_f32 v60, v101, v102
	v_cvt_pk_bf16_f32 v61, v107, v103
	global_store_dwordx4 v[62:63], v[58:61], off sc1
	s_nop 1
	v_mul_f32_e32 v58, v100, v100
	v_mul_f32_e32 v59, v65, v65
	v_fmac_f32_e32 v58, v106, v106
	v_fmac_f32_e32 v59, v64, v64
	v_add_f32_e32 v58, v58, v59
	v_mul_f32_e32 v59, v102, v102
	v_fmac_f32_e32 v59, v101, v101
	v_add_f32_e32 v58, v59, v58
	v_mul_f32_e32 v59, v103, v103
	v_fmac_f32_e32 v59, v107, v107
	v_add_f32_e32 v58, v59, v58
	s_waitcnt vmcnt(7)
	v_lshlrev_b32_e32 v59, 16, v90
	v_add_f32_e32 v54, v54, v59
	v_and_b32_e32 v59, 0xffff0000, v90
	v_add_f32_e32 v55, v55, v59
	v_lshlrev_b32_e32 v59, 16, v91
	v_add_f32_e32 v56, v56, v59
	v_and_b32_e32 v59, 0xffff0000, v91
	v_add_f32_e32 v57, v57, v59
	v_lshlrev_b32_e32 v59, 16, v92
	v_add_f32_e32 v59, v50, v59
	v_and_b32_e32 v50, 0xffff0000, v92
	v_add_f32_e32 v60, v51, v50
	v_lshlrev_b32_e32 v50, 16, v93
	v_add_f32_e32 v61, v52, v50
	v_and_b32_e32 v50, 0xffff0000, v93
	v_add_f32_e32 v64, v53, v50
	v_cvt_pk_bf16_f32 v50, v54, v55
	v_cvt_pk_bf16_f32 v51, v56, v57
	v_cvt_pk_bf16_f32 v52, v59, v60
	v_cvt_pk_bf16_f32 v53, v61, v64
	global_store_dwordx4 v[62:63], v[50:53], off offset:256 sc1
	s_nop 1
	v_mul_f32_e32 v50, v55, v55
	v_mul_f32_e32 v51, v57, v57
	v_fmac_f32_e32 v50, v54, v54
	v_fmac_f32_e32 v51, v56, v56
	v_add_f32_e32 v50, v50, v51
	v_mul_f32_e32 v51, v60, v60
	v_fmac_f32_e32 v51, v59, v59
	v_add_f32_e32 v50, v51, v50
	v_mul_f32_e32 v51, v64, v64
	v_fmac_f32_e32 v51, v61, v61
	v_add_f32_e32 v50, v51, v50
	v_add_f32_e32 v50, v58, v50
	ds_bpermute_b32 v51, v140, v50
	s_waitcnt lgkmcnt(0)
	v_add_f32_e32 v50, v50, v51
	ds_bpermute_b32 v51, v141, v50
	s_and_saveexec_b64 s[0:1], s[40:41]
	s_cbranch_execz .LBB0_175
	s_waitcnt lgkmcnt(0)
	v_add_f32_e32 v50, v50, v51
	v_mul_f32_e32 v50, 0x4b800000, v50
	v_rndne_f32_e32 v50, v50
	v_mul_f32_e32 v51, 0x2f800000, v50
	v_floor_f32_e32 v51, v51
	v_fmac_f32_e32 v50, 0xcf800000, v51
	v_cvt_u32_f32_e32 v50, v50
	v_cvt_u32_f32_e32 v51, v51
	global_atomic_add_x2 v[138:139], v[50:51], off offset:1024
.LBB0_175:
	s_or_b64 exec, exec, s[0:1]
	s_waitcnt vmcnt(7)
	v_lshlrev_b32_e32 v50, 16, v86
	v_add_f32_e32 v46, v46, v50
	v_and_b32_e32 v50, 0xffff0000, v86
	v_add_f32_e32 v47, v47, v50
	v_lshlrev_b32_e32 v50, 16, v87
	v_add_f32_e32 v48, v48, v50
	v_and_b32_e32 v50, 0xffff0000, v87
	v_add_f32_e32 v49, v49, v50
	v_lshlrev_b32_e32 v50, 16, v88
	v_add_f32_e32 v50, v42, v50
	v_and_b32_e32 v42, 0xffff0000, v88
	s_waitcnt lgkmcnt(0)
	v_add_f32_e32 v51, v43, v42
	v_lshlrev_b32_e32 v42, 16, v89
	v_add_f32_e32 v52, v44, v42
	v_and_b32_e32 v42, 0xffff0000, v89
	v_add_f32_e32 v53, v45, v42
	v_cvt_pk_bf16_f32 v42, v46, v47
	v_mul_f32_e32 v47, v47, v47
	v_fmac_f32_e32 v47, v46, v46
	v_mul_f32_e32 v46, v49, v49
	v_fmac_f32_e32 v46, v48, v48
	v_add_f32_e32 v46, v47, v46
	v_mul_f32_e32 v47, v51, v51
	v_fmac_f32_e32 v47, v50, v50
	v_add_f32_e32 v46, v47, v46
	v_mul_f32_e32 v47, v53, v53
	v_fmac_f32_e32 v47, v52, v52
	v_add_f32_e32 v46, v47, v46
	s_waitcnt vmcnt(6)
	v_lshlrev_b32_e32 v47, 16, v82
	v_add_f32_e32 v38, v38, v47
	v_and_b32_e32 v47, 0xffff0000, v82
	v_add_f32_e32 v39, v39, v47
	v_lshlrev_b32_e32 v47, 16, v83
	v_add_f32_e32 v47, v40, v47
	v_and_b32_e32 v40, 0xffff0000, v83
	v_cvt_pk_bf16_f32 v43, v48, v49
	v_add_f32_e32 v48, v41, v40
	v_lshlrev_b32_e32 v40, 16, v84
	v_add_f32_e32 v49, v34, v40
	v_and_b32_e32 v34, 0xffff0000, v84
	v_cvt_pk_bf16_f32 v44, v50, v51
	v_add_f32_e32 v50, v35, v34
	v_lshlrev_b32_e32 v34, 16, v85
	v_add_f32_e32 v51, v36, v34
	v_and_b32_e32 v34, 0xffff0000, v85
	v_cvt_pk_bf16_f32 v45, v52, v53
	v_add_f32_e32 v52, v37, v34
	v_mul_f32_e32 v34, v39, v39
	v_mul_f32_e32 v35, v48, v48
	v_fmac_f32_e32 v34, v38, v38
	v_fmac_f32_e32 v35, v47, v47
	v_add_f32_e32 v34, v34, v35
	v_mul_f32_e32 v35, v50, v50
	v_fmac_f32_e32 v35, v49, v49
	v_add_f32_e32 v34, v35, v34
	v_mul_f32_e32 v35, v52, v52
	v_fmac_f32_e32 v35, v51, v51
	v_add_f32_e32 v34, v35, v34
	v_add_f32_e32 v37, v46, v34
	ds_bpermute_b32 v46, v140, v37
	v_readlane_b32 s0, v254, 43
	v_readlane_b32 s1, v254, 44
	v_cvt_pk_bf16_f32 v36, v38, v39
	v_cvt_pk_bf16_f32 v38, v49, v50
	v_cvt_pk_bf16_f32 v39, v51, v52
	s_nop 1
	v_lshl_add_u64 v[34:35], s[0:1], 0, v[98:99]
	v_lshl_add_u64 v[40:41], v[174:175], 1, v[34:35]
	s_waitcnt lgkmcnt(0)
	v_add_f32_e32 v34, v37, v46
	ds_bpermute_b32 v35, v141, v34
	global_store_dwordx4 v[40:41], v[42:45], off sc1
	v_cvt_pk_bf16_f32 v37, v47, v48
	global_store_dwordx4 v[40:41], v[36:39], off offset:256 sc1
	s_and_saveexec_b64 s[0:1], s[40:41]
	s_cbranch_execz .LBB0_177
	s_waitcnt lgkmcnt(0)
	v_add_f32_e32 v34, v34, v35
	v_mul_f32_e32 v34, 0x4b800000, v34
	v_rndne_f32_e32 v34, v34
	v_mul_f32_e32 v35, 0x2f800000, v34
	v_floor_f32_e32 v35, v35
	v_fmac_f32_e32 v34, 0xcf800000, v35
	v_cvt_u32_f32_e32 v34, v34
	v_cvt_u32_f32_e32 v35, v35
	global_atomic_add_x2 v[138:139], v[34:35], off offset:1152
.LBB0_177:
	s_or_b64 exec, exec, s[0:1]
	s_waitcnt vmcnt(7)
	v_lshlrev_b32_e32 v34, 16, v78
	v_add_f32_e32 v30, v30, v34
	v_and_b32_e32 v34, 0xffff0000, v78
	v_add_f32_e32 v31, v31, v34
	v_lshlrev_b32_e32 v34, 16, v79
	v_add_f32_e32 v32, v32, v34
	v_and_b32_e32 v34, 0xffff0000, v79
	v_add_f32_e32 v33, v33, v34
	v_lshlrev_b32_e32 v34, 16, v80
	v_add_f32_e32 v34, v26, v34
	v_and_b32_e32 v26, 0xffff0000, v80
	s_waitcnt lgkmcnt(0)
	v_add_f32_e32 v35, v27, v26
	v_lshlrev_b32_e32 v26, 16, v81
	v_add_f32_e32 v36, v28, v26
	v_and_b32_e32 v26, 0xffff0000, v81
	v_add_f32_e32 v37, v29, v26
	v_cvt_pk_bf16_f32 v26, v30, v31
	v_mul_f32_e32 v31, v31, v31
	v_fmac_f32_e32 v31, v30, v30
	v_mul_f32_e32 v30, v33, v33
	v_fmac_f32_e32 v30, v32, v32
	v_add_f32_e32 v30, v31, v30
	v_mul_f32_e32 v31, v35, v35
	v_fmac_f32_e32 v31, v34, v34
	v_add_f32_e32 v30, v31, v30
	v_mul_f32_e32 v31, v37, v37
	v_fmac_f32_e32 v31, v36, v36
	v_add_f32_e32 v30, v31, v30
	s_waitcnt vmcnt(6)
	v_lshlrev_b32_e32 v31, 16, v74
	v_add_f32_e32 v22, v22, v31
	v_and_b32_e32 v31, 0xffff0000, v74
	v_add_f32_e32 v23, v23, v31
	v_lshlrev_b32_e32 v31, 16, v75
	v_add_f32_e32 v31, v24, v31
	v_and_b32_e32 v24, 0xffff0000, v75
	v_cvt_pk_bf16_f32 v27, v32, v33
	v_add_f32_e32 v32, v25, v24
	v_lshlrev_b32_e32 v24, 16, v76
	v_add_f32_e32 v33, v18, v24
	v_and_b32_e32 v18, 0xffff0000, v76
	v_cvt_pk_bf16_f32 v28, v34, v35
	v_add_f32_e32 v34, v19, v18
	v_lshlrev_b32_e32 v18, 16, v77
	v_add_f32_e32 v35, v20, v18
	v_and_b32_e32 v18, 0xffff0000, v77
	v_cvt_pk_bf16_f32 v29, v36, v37
	v_add_f32_e32 v36, v21, v18
	v_mul_f32_e32 v18, v23, v23
	v_mul_f32_e32 v19, v32, v32
	v_fmac_f32_e32 v18, v22, v22
	v_fmac_f32_e32 v19, v31, v31
	v_add_f32_e32 v18, v18, v19
	v_mul_f32_e32 v19, v34, v34
	v_fmac_f32_e32 v19, v33, v33
	v_add_f32_e32 v18, v19, v18
	v_mul_f32_e32 v19, v36, v36
	v_fmac_f32_e32 v19, v35, v35
	v_add_f32_e32 v18, v19, v18
	v_add_f32_e32 v21, v30, v18
	ds_bpermute_b32 v30, v140, v21
	v_readlane_b32 s0, v254, 43
	v_readlane_b32 s1, v254, 44
	v_cvt_pk_bf16_f32 v20, v22, v23
	v_cvt_pk_bf16_f32 v22, v33, v34
	v_cvt_pk_bf16_f32 v23, v35, v36
	s_nop 1
	v_lshl_add_u64 v[18:19], s[0:1], 0, v[96:97]
	v_lshl_add_u64 v[24:25], v[174:175], 1, v[18:19]
	s_waitcnt lgkmcnt(0)
	v_add_f32_e32 v18, v21, v30
	ds_bpermute_b32 v19, v141, v18
	global_store_dwordx4 v[24:25], v[26:29], off sc1
	v_cvt_pk_bf16_f32 v21, v31, v32
	global_store_dwordx4 v[24:25], v[20:23], off offset:256 sc1
	s_and_saveexec_b64 s[0:1], s[40:41]
	s_cbranch_execz .LBB0_179
	s_waitcnt lgkmcnt(0)
	v_add_f32_e32 v18, v18, v19
	v_mul_f32_e32 v18, 0x4b800000, v18
	v_rndne_f32_e32 v18, v18
	v_mul_f32_e32 v19, 0x2f800000, v18
	v_floor_f32_e32 v19, v19
	v_fmac_f32_e32 v18, 0xcf800000, v19
	v_cvt_u32_f32_e32 v18, v18
	v_cvt_u32_f32_e32 v19, v19
	global_atomic_add_x2 v[138:139], v[18:19], off offset:1280
.LBB0_179:
	s_or_b64 exec, exec, s[0:1]
	s_waitcnt vmcnt(7)
	v_lshlrev_b32_e32 v18, 16, v70
	v_add_f32_e32 v14, v14, v18
	v_and_b32_e32 v18, 0xffff0000, v70
	v_add_f32_e32 v15, v15, v18
	v_lshlrev_b32_e32 v18, 16, v71
	v_add_f32_e32 v16, v16, v18
	v_and_b32_e32 v18, 0xffff0000, v71
	v_add_f32_e32 v17, v17, v18
	v_lshlrev_b32_e32 v18, 16, v72
	v_add_f32_e32 v18, v10, v18
	v_and_b32_e32 v10, 0xffff0000, v72
	s_waitcnt lgkmcnt(0)
	v_add_f32_e32 v19, v11, v10
	v_lshlrev_b32_e32 v10, 16, v73
	v_add_f32_e32 v20, v12, v10
	v_and_b32_e32 v10, 0xffff0000, v73
	v_add_f32_e32 v21, v13, v10
	v_cvt_pk_bf16_f32 v10, v14, v15
	v_mul_f32_e32 v15, v15, v15
	v_fmac_f32_e32 v15, v14, v14
	v_mul_f32_e32 v14, v17, v17
	v_fmac_f32_e32 v14, v16, v16
	v_add_f32_e32 v14, v15, v14
	v_mul_f32_e32 v15, v19, v19
	v_fmac_f32_e32 v15, v18, v18
	v_add_f32_e32 v14, v15, v14
	v_mul_f32_e32 v15, v21, v21
	v_fmac_f32_e32 v15, v20, v20
	v_add_f32_e32 v14, v15, v14
	s_waitcnt vmcnt(6)
	v_lshlrev_b32_e32 v15, 16, v66
	v_add_f32_e32 v6, v6, v15
	v_and_b32_e32 v15, 0xffff0000, v66
	v_add_f32_e32 v7, v7, v15
	v_lshlrev_b32_e32 v15, 16, v67
	v_add_f32_e32 v15, v8, v15
	v_and_b32_e32 v8, 0xffff0000, v67
	v_cvt_pk_bf16_f32 v11, v16, v17
	v_add_f32_e32 v16, v9, v8
	v_lshlrev_b32_e32 v8, 16, v68
	v_add_f32_e32 v17, v2, v8
	v_and_b32_e32 v2, 0xffff0000, v68
	v_cvt_pk_bf16_f32 v12, v18, v19
	v_add_f32_e32 v18, v3, v2
	v_lshlrev_b32_e32 v2, 16, v69
	v_add_f32_e32 v19, v4, v2
	v_and_b32_e32 v2, 0xffff0000, v69
	v_cvt_pk_bf16_f32 v13, v20, v21
	v_add_f32_e32 v20, v5, v2
	v_mul_f32_e32 v2, v7, v7
	v_mul_f32_e32 v3, v16, v16
	v_fmac_f32_e32 v2, v6, v6
	v_fmac_f32_e32 v3, v15, v15
	v_add_f32_e32 v2, v2, v3
	v_mul_f32_e32 v3, v18, v18
	v_fmac_f32_e32 v3, v17, v17
	v_add_f32_e32 v2, v3, v2
	v_mul_f32_e32 v3, v20, v20
	v_fmac_f32_e32 v3, v19, v19
	v_add_f32_e32 v2, v3, v2
	v_add_f32_e32 v5, v14, v2
	ds_bpermute_b32 v14, v140, v5
	v_readlane_b32 s0, v254, 43
	v_readlane_b32 s1, v254, 44
	v_cvt_pk_bf16_f32 v4, v6, v7
	v_cvt_pk_bf16_f32 v6, v17, v18
	v_cvt_pk_bf16_f32 v7, v19, v20
	s_nop 1
	v_lshl_add_u64 v[2:3], s[0:1], 0, v[94:95]
	v_lshl_add_u64 v[8:9], v[174:175], 1, v[2:3]
	s_waitcnt lgkmcnt(0)
	v_add_f32_e32 v2, v5, v14
	ds_bpermute_b32 v3, v141, v2
	global_store_dwordx4 v[8:9], v[10:13], off sc1
	v_cvt_pk_bf16_f32 v5, v15, v16
	global_store_dwordx4 v[8:9], v[4:7], off offset:256 sc1
	s_and_saveexec_b64 s[0:1], s[40:41]
	s_cbranch_execz .LBB0_181
	s_waitcnt lgkmcnt(0)
	v_add_f32_e32 v2, v2, v3
	v_mul_f32_e32 v2, 0x4b800000, v2
	v_rndne_f32_e32 v2, v2
	v_mul_f32_e32 v3, 0x2f800000, v2
	v_floor_f32_e32 v3, v3
	v_fmac_f32_e32 v2, 0xcf800000, v3
	v_cvt_u32_f32_e32 v2, v2
	v_cvt_u32_f32_e32 v3, v3
	global_atomic_add_x2 v[138:139], v[2:3], off offset:1408

.LBB0_217:
	s_waitcnt vmcnt(0)
	v_cvt_f32_ubyte1_e32 v195, v192
	v_cvt_f32_ubyte0_e32 v194, v192
	v_cvt_f32_ubyte3_e32 v197, v192
	v_cvt_f32_ubyte2_e32 v196, v192
	v_lshlrev_b64 v[206:207], 11, v[158:159]
	v_pk_mul_f32 v[198:199], v[122:123], v[194:195]
	v_cvt_f32_ubyte1_e32 v195, v193
	v_cvt_f32_ubyte0_e32 v194, v193
	v_pk_mul_f32 v[200:201], v[124:125], v[196:197]
	v_cvt_f32_ubyte3_e32 v197, v193
	v_cvt_f32_ubyte2_e32 v196, v193
	v_pk_mul_f32 v[194:195], v[126:127], v[194:195]
	v_pk_mul_f32 v[196:197], v[128:129], v[196:197]
	s_mov_b64 s[2:3], -1
	s_and_b64 vcc, exec, s[0:1]
	v_lshl_add_u64 v[192:193], s[36:37], 0, v[206:207]
	v_lshlrev_b32_e32 v0, 1, v0
	s_cbranch_vccz .LBB0_219
	s_mov_b32 s2, 0x3b808081
	v_pk_mul_f32 v[206:207], v[200:201], s[2:3] op_sel_hi:[1,0]
	v_pk_mul_f32 v[224:225], v[198:199], s[2:3] op_sel_hi:[1,0]
	v_pk_mul_f32 v[226:227], v[194:195], s[2:3] op_sel_hi:[1,0]
	v_cvt_pk_bf16_f32 v224, v224, v225
	v_cvt_pk_bf16_f32 v225, v206, v207
	v_lshl_add_u64 v[206:207], v[192:193], 0, v[0:1]
	v_pk_mul_f32 v[228:229], v[196:197], s[2:3] op_sel_hi:[1,0]
	v_cvt_pk_bf16_f32 v226, v226, v227
	s_mov_b64 s[2:3], 0
	v_cvt_pk_bf16_f32 v227, v228, v229
	global_store_dwordx4 v[206:207], v[224:227], off sc1

.LBB0_221:
	v_cvt_f32_ubyte1_e32 v195, v190
	v_cvt_f32_ubyte0_e32 v194, v190
	v_pk_mul_f32 v[196:197], v[90:91], v[194:195]
	v_cvt_f32_ubyte1_e32 v195, v191
	v_cvt_f32_ubyte0_e32 v194, v191
	v_cvt_f32_ubyte3_e32 v199, v190
	v_cvt_f32_ubyte2_e32 v198, v190
	v_cvt_f32_ubyte3_e32 v201, v191
	v_cvt_f32_ubyte2_e32 v200, v191
	v_cndmask_b32_e64 v159, 0, 1, s[0:1]
	v_pk_mul_f32 v[194:195], v[94:95], v[194:195]
	v_pk_mul_f32 v[198:199], v[92:93], v[198:199]
	v_pk_mul_f32 v[190:191], v[96:97], v[200:201]
	v_cmp_ne_u32_e64 s[42:43], 1, v159
	s_andn2_b64 vcc, exec, s[0:1]
	s_mov_b64 s[0:1], -1
	s_cbranch_vccnz .LBB0_223
	s_mov_b32 s0, 0x3b808081
	v_pk_mul_f32 v[200:201], v[198:199], s[0:1] op_sel_hi:[1,0]
	v_pk_mul_f32 v[206:207], v[196:197], s[0:1] op_sel_hi:[1,0]
	v_pk_mul_f32 v[228:229], v[190:191], s[0:1] op_sel_hi:[1,0]
	v_pk_mul_f32 v[226:227], v[194:195], s[0:1] op_sel_hi:[1,0]
	v_lshl_add_u64 v[192:193], v[192:193], 0, v[0:1]
	s_mov_b64 s[0:1], 0
	v_cvt_pk_bf16_f32 v224, v206, v207
	v_cvt_pk_bf16_f32 v225, v200, v201
	v_cvt_pk_bf16_f32 v226, v226, v227
	v_cvt_pk_bf16_f32 v227, v228, v229
	global_store_dwordx4 v[192:193], v[224:227], off offset:256 sc1

.LBB0_225:
	v_ashrrev_i32_e32 v189, 31, v188
	v_lshlrev_b64 v[196:197], 11, v[188:189]
	v_cvt_f32_ubyte1_e32 v189, v186
	v_cvt_f32_ubyte0_e32 v188, v186
	v_cvt_f32_ubyte3_e32 v191, v186
	v_cvt_f32_ubyte2_e32 v190, v186
	v_pk_mul_f32 v[192:193], v[114:115], v[188:189]
	v_cvt_f32_ubyte1_e32 v189, v187
	v_cvt_f32_ubyte0_e32 v188, v187
	v_pk_mul_f32 v[194:195], v[116:117], v[190:191]
	v_cvt_f32_ubyte3_e32 v191, v187
	v_cvt_f32_ubyte2_e32 v190, v187
	v_pk_mul_f32 v[188:189], v[118:119], v[188:189]
	v_pk_mul_f32 v[190:191], v[120:121], v[190:191]
	s_mov_b64 s[0:1], -1
	s_and_b64 vcc, exec, s[42:43]
	v_lshl_add_u64 v[186:187], s[36:37], 0, v[196:197]
	s_cbranch_vccnz .LBB0_227
	s_mov_b32 s0, 0x3b808081
	v_pk_mul_f32 v[198:199], v[194:195], s[0:1] op_sel_hi:[1,0]
	v_pk_mul_f32 v[196:197], v[192:193], s[0:1] op_sel_hi:[1,0]
	v_pk_mul_f32 v[200:201], v[190:191], s[0:1] op_sel_hi:[1,0]
	v_pk_mul_f32 v[206:207], v[188:189], s[0:1] op_sel_hi:[1,0]
	v_cvt_pk_bf16_f32 v196, v196, v197
	v_cvt_pk_bf16_f32 v197, v198, v199
	v_cvt_pk_bf16_f32 v199, v200, v201
	v_lshl_add_u64 v[200:201], v[186:187], 0, v[0:1]
	s_mov_b64 s[0:1], 0
	v_cvt_pk_bf16_f32 v198, v206, v207
	global_store_dwordx4 v[200:201], v[196:199], off sc1

.LBB0_229:
	v_cvt_f32_ubyte1_e32 v189, v184
	v_cvt_f32_ubyte0_e32 v188, v184
	v_pk_mul_f32 v[190:191], v[82:83], v[188:189]
	v_cvt_f32_ubyte1_e32 v189, v185
	v_cvt_f32_ubyte0_e32 v188, v185
	v_cvt_f32_ubyte3_e32 v193, v184
	v_cvt_f32_ubyte2_e32 v192, v184
	v_cvt_f32_ubyte3_e32 v195, v185
	v_cvt_f32_ubyte2_e32 v194, v185
	v_pk_mul_f32 v[188:189], v[86:87], v[188:189]
	v_pk_mul_f32 v[192:193], v[84:85], v[192:193]
	v_pk_mul_f32 v[184:185], v[88:89], v[194:195]
	s_and_b64 vcc, exec, s[42:43]
	s_mov_b64 s[0:1], -1
	s_cbranch_vccnz .LBB0_231
	s_mov_b32 s0, 0x3b808081
	v_pk_mul_f32 v[196:197], v[192:193], s[0:1] op_sel_hi:[1,0]
	v_pk_mul_f32 v[194:195], v[190:191], s[0:1] op_sel_hi:[1,0]
	v_pk_mul_f32 v[198:199], v[184:185], s[0:1] op_sel_hi:[1,0]
	v_pk_mul_f32 v[200:201], v[188:189], s[0:1] op_sel_hi:[1,0]
	v_lshl_add_u64 v[186:187], v[186:187], 0, v[0:1]
	s_mov_b64 s[0:1], 0
	v_cvt_pk_bf16_f32 v194, v194, v195
	v_cvt_pk_bf16_f32 v195, v196, v197
	v_cvt_pk_bf16_f32 v196, v200, v201
	v_cvt_pk_bf16_f32 v197, v198, v199
	global_store_dwordx4 v[186:187], v[194:197], off offset:256 sc1

.LBB0_233:
	v_ashrrev_i32_e32 v183, 31, v182
	v_lshlrev_b64 v[190:191], 11, v[182:183]
	v_cvt_f32_ubyte1_e32 v183, v180
	v_cvt_f32_ubyte0_e32 v182, v180
	v_cvt_f32_ubyte3_e32 v185, v180
	v_cvt_f32_ubyte2_e32 v184, v180
	v_pk_mul_f32 v[186:187], v[106:107], v[182:183]
	v_cvt_f32_ubyte1_e32 v183, v181
	v_cvt_f32_ubyte0_e32 v182, v181
	v_pk_mul_f32 v[188:189], v[108:109], v[184:185]
	v_cvt_f32_ubyte3_e32 v185, v181
	v_cvt_f32_ubyte2_e32 v184, v181
	v_pk_mul_f32 v[182:183], v[110:111], v[182:183]
	v_pk_mul_f32 v[184:185], v[112:113], v[184:185]
	s_mov_b64 s[0:1], -1
	s_and_b64 vcc, exec, s[42:43]
	v_lshl_add_u64 v[180:181], s[36:37], 0, v[190:191]
	s_cbranch_vccnz .LBB0_235
	s_mov_b32 s0, 0x3b808081
	v_pk_mul_f32 v[192:193], v[188:189], s[0:1] op_sel_hi:[1,0]
	v_pk_mul_f32 v[190:191], v[186:187], s[0:1] op_sel_hi:[1,0]
	v_pk_mul_f32 v[194:195], v[184:185], s[0:1] op_sel_hi:[1,0]
	v_pk_mul_f32 v[196:197], v[182:183], s[0:1] op_sel_hi:[1,0]
	v_cvt_pk_bf16_f32 v190, v190, v191
	v_cvt_pk_bf16_f32 v191, v192, v193
	v_cvt_pk_bf16_f32 v193, v194, v195
	v_lshl_add_u64 v[194:195], v[180:181], 0, v[0:1]
	s_mov_b64 s[0:1], 0
	v_cvt_pk_bf16_f32 v192, v196, v197
	global_store_dwordx4 v[194:195], v[190:193], off sc1

.LBB0_237:
	v_cvt_f32_ubyte1_e32 v183, v178
	v_cvt_f32_ubyte0_e32 v182, v178
	v_pk_mul_f32 v[184:185], v[74:75], v[182:183]
	v_cvt_f32_ubyte1_e32 v183, v179
	v_cvt_f32_ubyte0_e32 v182, v179
	v_cvt_f32_ubyte3_e32 v187, v178
	v_cvt_f32_ubyte2_e32 v186, v178
	v_cvt_f32_ubyte3_e32 v189, v179
	v_cvt_f32_ubyte2_e32 v188, v179
	v_pk_mul_f32 v[182:183], v[78:79], v[182:183]
	v_pk_mul_f32 v[186:187], v[76:77], v[186:187]
	v_pk_mul_f32 v[178:179], v[80:81], v[188:189]
	s_and_b64 vcc, exec, s[42:43]
	s_mov_b64 s[0:1], -1
	s_cbranch_vccnz .LBB0_239
	s_mov_b32 s0, 0x3b808081
	v_pk_mul_f32 v[190:191], v[186:187], s[0:1] op_sel_hi:[1,0]
	v_pk_mul_f32 v[188:189], v[184:185], s[0:1] op_sel_hi:[1,0]
	v_pk_mul_f32 v[192:193], v[178:179], s[0:1] op_sel_hi:[1,0]
	v_pk_mul_f32 v[194:195], v[182:183], s[0:1] op_sel_hi:[1,0]
	v_lshl_add_u64 v[180:181], v[180:181], 0, v[0:1]
	s_mov_b64 s[0:1], 0
	v_cvt_pk_bf16_f32 v188, v188, v189
	v_cvt_pk_bf16_f32 v189, v190, v191
	v_cvt_pk_bf16_f32 v190, v194, v195
	v_cvt_pk_bf16_f32 v191, v192, v193
	global_store_dwordx4 v[180:181], v[188:191], off offset:256 sc1

.LBB0_241:
	v_ashrrev_i32_e32 v177, 31, v176
	v_lshlrev_b64 v[184:185], 11, v[176:177]
	v_cvt_f32_ubyte1_e32 v177, v174
	v_cvt_f32_ubyte0_e32 v176, v174
	v_cvt_f32_ubyte3_e32 v179, v174
	v_cvt_f32_ubyte2_e32 v178, v174
	v_pk_mul_f32 v[180:181], v[98:99], v[176:177]
	v_cvt_f32_ubyte1_e32 v177, v175
	v_cvt_f32_ubyte0_e32 v176, v175
	v_pk_mul_f32 v[182:183], v[100:101], v[178:179]
	v_cvt_f32_ubyte3_e32 v179, v175
	v_cvt_f32_ubyte2_e32 v178, v175
	v_pk_mul_f32 v[176:177], v[102:103], v[176:177]
	v_pk_mul_f32 v[178:179], v[104:105], v[178:179]
	s_mov_b64 s[0:1], -1
	s_and_b64 vcc, exec, s[42:43]
	v_lshl_add_u64 v[174:175], s[36:37], 0, v[184:185]
	s_cbranch_vccnz .LBB0_243
	s_mov_b32 s0, 0x3b808081
	v_pk_mul_f32 v[186:187], v[182:183], s[0:1] op_sel_hi:[1,0]
	v_pk_mul_f32 v[184:185], v[180:181], s[0:1] op_sel_hi:[1,0]
	v_pk_mul_f32 v[188:189], v[178:179], s[0:1] op_sel_hi:[1,0]
	v_pk_mul_f32 v[190:191], v[176:177], s[0:1] op_sel_hi:[1,0]
	v_cvt_pk_bf16_f32 v184, v184, v185
	v_cvt_pk_bf16_f32 v185, v186, v187
	v_cvt_pk_bf16_f32 v187, v188, v189
	v_lshl_add_u64 v[188:189], v[174:175], 0, v[0:1]
	s_mov_b64 s[0:1], 0
	v_cvt_pk_bf16_f32 v186, v190, v191
	global_store_dwordx4 v[188:189], v[184:187], off sc1

.LBB0_245:
	v_cvt_f32_ubyte1_e32 v177, v172
	v_cvt_f32_ubyte0_e32 v176, v172
	v_pk_mul_f32 v[178:179], v[66:67], v[176:177]
	v_cvt_f32_ubyte1_e32 v177, v173
	v_cvt_f32_ubyte0_e32 v176, v173
	v_cvt_f32_ubyte3_e32 v181, v172
	v_cvt_f32_ubyte2_e32 v180, v172
	v_cvt_f32_ubyte3_e32 v183, v173
	v_cvt_f32_ubyte2_e32 v182, v173
	v_pk_mul_f32 v[176:177], v[70:71], v[176:177]
	v_pk_mul_f32 v[180:181], v[68:69], v[180:181]
	v_pk_mul_f32 v[172:173], v[72:73], v[182:183]
	s_and_b64 vcc, exec, s[42:43]
	s_mov_b64 s[0:1], -1
	s_cbranch_vccnz .LBB0_247
	s_mov_b32 s0, 0x3b808081
	v_pk_mul_f32 v[184:185], v[180:181], s[0:1] op_sel_hi:[1,0]
	v_pk_mul_f32 v[182:183], v[178:179], s[0:1] op_sel_hi:[1,0]
	v_pk_mul_f32 v[186:187], v[172:173], s[0:1] op_sel_hi:[1,0]
	v_pk_mul_f32 v[188:189], v[176:177], s[0:1] op_sel_hi:[1,0]
	v_lshl_add_u64 v[174:175], v[174:175], 0, v[0:1]
	s_mov_b64 s[0:1], 0
	v_cvt_pk_bf16_f32 v182, v182, v183
	v_cvt_pk_bf16_f32 v183, v184, v185
	v_cvt_pk_bf16_f32 v184, v188, v189
	v_cvt_pk_bf16_f32 v185, v186, v187
	global_store_dwordx4 v[174:175], v[182:185], off offset:256 sc1

.LBB0_265:
	v_ashrrev_i32_e32 v191, 31, v190
	v_lshlrev_b64 v[198:199], 11, v[190:191]
	s_waitcnt vmcnt(7)
	v_cvt_f32_ubyte1_e32 v191, v188
	v_cvt_f32_ubyte0_e32 v190, v188
	v_cvt_f32_ubyte1_e32 v193, v189
	v_cvt_f32_ubyte0_e32 v192, v189
	v_cvt_f32_ubyte3_e32 v195, v188
	v_cvt_f32_ubyte2_e32 v194, v188
	v_cvt_f32_ubyte3_e32 v197, v189
	v_cvt_f32_ubyte2_e32 v196, v189
	v_pk_mul_f32 v[190:191], v[62:63], v[190:191]
	v_pk_mul_f32 v[192:193], v[58:59], v[192:193]
	v_pk_mul_f32 v[194:195], v[64:65], v[194:195]
	v_pk_mul_f32 v[196:197], v[60:61], v[196:197]
	s_mov_b64 s[0:1], -1
	s_and_b64 vcc, exec, s[42:43]
	v_lshl_add_u64 v[188:189], s[36:37], 0, v[198:199]
	s_cbranch_vccnz .LBB0_267
	s_mov_b32 s0, 0x3b808081
	v_pk_mul_f32 v[200:201], v[194:195], s[0:1] op_sel_hi:[1,0]
	v_pk_mul_f32 v[198:199], v[190:191], s[0:1] op_sel_hi:[1,0]
	v_pk_mul_f32 v[206:207], v[196:197], s[0:1] op_sel_hi:[1,0]
	v_pk_mul_f32 v[224:225], v[192:193], s[0:1] op_sel_hi:[1,0]
	v_cvt_pk_bf16_f32 v198, v198, v199
	v_cvt_pk_bf16_f32 v199, v200, v201
	v_cvt_pk_bf16_f32 v201, v206, v207
	v_lshl_add_u64 v[206:207], v[188:189], 0, v[0:1]
	s_mov_b64 s[0:1], 0
	v_cvt_pk_bf16_f32 v200, v224, v225
	global_store_dwordx4 v[206:207], v[198:201], off sc1

.LBB0_269:
	s_waitcnt vmcnt(6)
	v_cvt_f32_ubyte1_e32 v157, v186
	v_cvt_f32_ubyte0_e32 v156, v186
	v_cvt_f32_ubyte1_e32 v191, v187
	v_cvt_f32_ubyte0_e32 v190, v187
	v_cvt_f32_ubyte3_e32 v193, v186
	v_cvt_f32_ubyte2_e32 v192, v186
	v_cvt_f32_ubyte3_e32 v195, v187
	v_cvt_f32_ubyte2_e32 v194, v187
	v_pk_mul_f32 v[156:157], v[30:31], v[156:157]
	v_pk_mul_f32 v[190:191], v[26:27], v[190:191]
	v_pk_mul_f32 v[192:193], v[32:33], v[192:193]
	v_pk_mul_f32 v[186:187], v[28:29], v[194:195]
	s_and_b64 vcc, exec, s[42:43]
	s_mov_b64 s[0:1], -1
	s_cbranch_vccnz .LBB0_271
	s_mov_b32 s0, 0x3b808081
	v_pk_mul_f32 v[196:197], v[192:193], s[0:1] op_sel_hi:[1,0]
	v_pk_mul_f32 v[194:195], v[156:157], s[0:1] op_sel_hi:[1,0]
	v_pk_mul_f32 v[198:199], v[186:187], s[0:1] op_sel_hi:[1,0]
	v_pk_mul_f32 v[200:201], v[190:191], s[0:1] op_sel_hi:[1,0]
	v_lshl_add_u64 v[188:189], v[188:189], 0, v[0:1]
	s_mov_b64 s[0:1], 0
	v_cvt_pk_bf16_f32 v194, v194, v195
	v_cvt_pk_bf16_f32 v195, v196, v197
	v_cvt_pk_bf16_f32 v196, v200, v201
	v_cvt_pk_bf16_f32 v197, v198, v199
	global_store_dwordx4 v[188:189], v[194:197], off offset:256 sc1

.LBB0_273:
	v_ashrrev_i32_e32 v185, 31, v184
	v_lshlrev_b64 v[154:155], 11, v[184:185]
	s_waitcnt vmcnt(5)
	v_cvt_f32_ubyte1_e32 v157, v182
	v_cvt_f32_ubyte0_e32 v156, v182
	v_cvt_f32_ubyte1_e32 v185, v183
	v_cvt_f32_ubyte0_e32 v184, v183
	v_cvt_f32_ubyte3_e32 v187, v182
	v_cvt_f32_ubyte2_e32 v186, v182
	v_cvt_f32_ubyte3_e32 v189, v183
	v_cvt_f32_ubyte2_e32 v188, v183
	v_pk_mul_f32 v[156:157], v[54:55], v[156:157]
	v_pk_mul_f32 v[184:185], v[50:51], v[184:185]
	v_pk_mul_f32 v[186:187], v[56:57], v[186:187]
	v_pk_mul_f32 v[182:183], v[52:53], v[188:189]
	s_mov_b64 s[0:1], -1
	s_and_b64 vcc, exec, s[42:43]
	v_lshl_add_u64 v[154:155], s[36:37], 0, v[154:155]
	s_cbranch_vccnz .LBB0_275
	s_mov_b32 s0, 0x3b808081
	v_pk_mul_f32 v[190:191], v[186:187], s[0:1] op_sel_hi:[1,0]
	v_pk_mul_f32 v[188:189], v[156:157], s[0:1] op_sel_hi:[1,0]
	v_pk_mul_f32 v[192:193], v[182:183], s[0:1] op_sel_hi:[1,0]
	v_pk_mul_f32 v[194:195], v[184:185], s[0:1] op_sel_hi:[1,0]
	v_cvt_pk_bf16_f32 v188, v188, v189
	v_cvt_pk_bf16_f32 v189, v190, v191
	v_cvt_pk_bf16_f32 v191, v192, v193
	v_lshl_add_u64 v[192:193], v[154:155], 0, v[0:1]
	s_mov_b64 s[0:1], 0
	v_cvt_pk_bf16_f32 v190, v194, v195
	global_store_dwordx4 v[192:193], v[188:191], off sc1

.LBB0_277:
	s_waitcnt vmcnt(4)
	v_cvt_f32_ubyte1_e32 v153, v180
	v_cvt_f32_ubyte0_e32 v152, v180
	v_cvt_f32_ubyte1_e32 v157, v181
	v_cvt_f32_ubyte0_e32 v156, v181
	v_cvt_f32_ubyte3_e32 v183, v180
	v_cvt_f32_ubyte2_e32 v182, v180
	v_cvt_f32_ubyte3_e32 v185, v181
	v_cvt_f32_ubyte2_e32 v184, v181
	v_pk_mul_f32 v[152:153], v[22:23], v[152:153]
	v_pk_mul_f32 v[156:157], v[18:19], v[156:157]
	v_pk_mul_f32 v[182:183], v[24:25], v[182:183]
	v_pk_mul_f32 v[180:181], v[20:21], v[184:185]
	s_and_b64 vcc, exec, s[42:43]
	s_mov_b64 s[0:1], -1
	s_cbranch_vccnz .LBB0_279
	s_mov_b32 s0, 0x3b808081
	v_pk_mul_f32 v[186:187], v[182:183], s[0:1] op_sel_hi:[1,0]
	v_pk_mul_f32 v[184:185], v[152:153], s[0:1] op_sel_hi:[1,0]
	v_pk_mul_f32 v[188:189], v[180:181], s[0:1] op_sel_hi:[1,0]
	v_pk_mul_f32 v[190:191], v[156:157], s[0:1] op_sel_hi:[1,0]
	v_lshl_add_u64 v[154:155], v[154:155], 0, v[0:1]
	s_mov_b64 s[0:1], 0
	v_cvt_pk_bf16_f32 v184, v184, v185
	v_cvt_pk_bf16_f32 v185, v186, v187
	v_cvt_pk_bf16_f32 v186, v190, v191
	v_cvt_pk_bf16_f32 v187, v188, v189
	global_store_dwordx4 v[154:155], v[184:187], off offset:256 sc1

.LBB0_281:
	v_ashrrev_i32_e32 v179, 31, v178
	v_lshlrev_b64 v[150:151], 11, v[178:179]
	s_waitcnt vmcnt(3)
	v_cvt_f32_ubyte1_e32 v153, v176
	v_cvt_f32_ubyte0_e32 v152, v176
	v_cvt_f32_ubyte1_e32 v155, v177
	v_cvt_f32_ubyte0_e32 v154, v177
	v_cvt_f32_ubyte3_e32 v157, v176
	v_cvt_f32_ubyte2_e32 v156, v176
	v_cvt_f32_ubyte3_e32 v179, v177
	v_cvt_f32_ubyte2_e32 v178, v177
	v_pk_mul_f32 v[152:153], v[46:47], v[152:153]
	v_pk_mul_f32 v[154:155], v[42:43], v[154:155]
	v_pk_mul_f32 v[156:157], v[48:49], v[156:157]
	v_pk_mul_f32 v[176:177], v[44:45], v[178:179]
	s_mov_b64 s[0:1], -1
	s_and_b64 vcc, exec, s[42:43]
	v_lshl_add_u64 v[150:151], s[36:37], 0, v[150:151]
	s_cbranch_vccnz .LBB0_283
	s_mov_b32 s0, 0x3b808081
	v_pk_mul_f32 v[180:181], v[156:157], s[0:1] op_sel_hi:[1,0]
	v_pk_mul_f32 v[178:179], v[152:153], s[0:1] op_sel_hi:[1,0]
	v_pk_mul_f32 v[182:183], v[176:177], s[0:1] op_sel_hi:[1,0]
	v_pk_mul_f32 v[184:185], v[154:155], s[0:1] op_sel_hi:[1,0]
	v_cvt_pk_bf16_f32 v178, v178, v179
	v_cvt_pk_bf16_f32 v179, v180, v181
	v_cvt_pk_bf16_f32 v181, v182, v183
	v_lshl_add_u64 v[182:183], v[150:151], 0, v[0:1]
	s_mov_b64 s[0:1], 0
	v_cvt_pk_bf16_f32 v180, v184, v185
	global_store_dwordx4 v[182:183], v[178:181], off sc1

.LBB0_285:
	s_waitcnt vmcnt(2)
	v_cvt_f32_ubyte1_e32 v149, v174
	v_cvt_f32_ubyte0_e32 v148, v174
	v_cvt_f32_ubyte1_e32 v153, v175
	v_cvt_f32_ubyte0_e32 v152, v175
	v_cvt_f32_ubyte3_e32 v155, v174
	v_cvt_f32_ubyte2_e32 v154, v174
	v_cvt_f32_ubyte3_e32 v157, v175
	v_cvt_f32_ubyte2_e32 v156, v175
	v_pk_mul_f32 v[148:149], v[14:15], v[148:149]
	v_pk_mul_f32 v[152:153], v[10:11], v[152:153]
	v_pk_mul_f32 v[154:155], v[16:17], v[154:155]
	v_pk_mul_f32 v[156:157], v[12:13], v[156:157]
	s_and_b64 vcc, exec, s[42:43]
	s_mov_b64 s[0:1], -1
	s_cbranch_vccnz .LBB0_287
	s_mov_b32 s0, 0x3b808081
	v_pk_mul_f32 v[176:177], v[154:155], s[0:1] op_sel_hi:[1,0]
	v_pk_mul_f32 v[174:175], v[148:149], s[0:1] op_sel_hi:[1,0]
	v_pk_mul_f32 v[178:179], v[156:157], s[0:1] op_sel_hi:[1,0]
	v_pk_mul_f32 v[180:181], v[152:153], s[0:1] op_sel_hi:[1,0]
	v_lshl_add_u64 v[150:151], v[150:151], 0, v[0:1]
	s_mov_b64 s[0:1], 0
	v_cvt_pk_bf16_f32 v174, v174, v175
	v_cvt_pk_bf16_f32 v175, v176, v177
	v_cvt_pk_bf16_f32 v176, v180, v181
	v_cvt_pk_bf16_f32 v177, v178, v179
	global_store_dwordx4 v[150:151], v[174:177], off offset:256 sc1

.LBB0_289:
	v_ashrrev_i32_e32 v173, 31, v172
	v_lshlrev_b64 v[146:147], 11, v[172:173]
	s_waitcnt vmcnt(1)
	v_cvt_f32_ubyte1_e32 v149, v170
	v_cvt_f32_ubyte0_e32 v148, v170
	v_cvt_f32_ubyte1_e32 v151, v171
	v_cvt_f32_ubyte0_e32 v150, v171
	v_cvt_f32_ubyte3_e32 v153, v170
	v_cvt_f32_ubyte2_e32 v152, v170
	v_cvt_f32_ubyte3_e32 v155, v171
	v_cvt_f32_ubyte2_e32 v154, v171
	v_pk_mul_f32 v[148:149], v[38:39], v[148:149]
	v_pk_mul_f32 v[150:151], v[34:35], v[150:151]
	v_pk_mul_f32 v[152:153], v[40:41], v[152:153]
	v_pk_mul_f32 v[154:155], v[36:37], v[154:155]
	s_mov_b64 s[0:1], -1
	s_and_b64 vcc, exec, s[42:43]
	v_lshl_add_u64 v[146:147], s[36:37], 0, v[146:147]
	s_cbranch_vccnz .LBB0_291
	s_mov_b32 s0, 0x3b808081
	v_pk_mul_f32 v[156:157], v[152:153], s[0:1] op_sel_hi:[1,0]
	v_pk_mul_f32 v[170:171], v[148:149], s[0:1] op_sel_hi:[1,0]
	v_pk_mul_f32 v[174:175], v[154:155], s[0:1] op_sel_hi:[1,0]
	v_pk_mul_f32 v[172:173], v[150:151], s[0:1] op_sel_hi:[1,0]
	v_cvt_pk_bf16_f32 v170, v170, v171
	v_cvt_pk_bf16_f32 v171, v156, v157
	v_lshl_add_u64 v[156:157], v[146:147], 0, v[0:1]
	s_mov_b64 s[0:1], 0
	v_cvt_pk_bf16_f32 v172, v172, v173
	v_cvt_pk_bf16_f32 v173, v174, v175
	global_store_dwordx4 v[156:157], v[170:173], off sc1

.LBB0_293:
	s_waitcnt vmcnt(0)
	v_cvt_f32_ubyte1_e32 v145, v158
	v_cvt_f32_ubyte0_e32 v144, v158
	v_cvt_f32_ubyte1_e32 v149, v159
	v_cvt_f32_ubyte0_e32 v148, v159
	v_cvt_f32_ubyte3_e32 v151, v158
	v_cvt_f32_ubyte2_e32 v150, v158
	v_cvt_f32_ubyte3_e32 v153, v159
	v_cvt_f32_ubyte2_e32 v152, v159
	v_pk_mul_f32 v[144:145], v[6:7], v[144:145]
	v_pk_mul_f32 v[148:149], v[2:3], v[148:149]
	v_pk_mul_f32 v[150:151], v[8:9], v[150:151]
	v_pk_mul_f32 v[152:153], v[4:5], v[152:153]
	s_and_b64 vcc, exec, s[42:43]
	s_mov_b64 s[0:1], -1
	s_cbranch_vccnz .LBB0_296
	s_mov_b32 s0, 0x3b808081
	v_pk_mul_f32 v[156:157], v[150:151], s[0:1] op_sel_hi:[1,0]
	v_pk_mul_f32 v[154:155], v[144:145], s[0:1] op_sel_hi:[1,0]
	v_pk_mul_f32 v[158:159], v[152:153], s[0:1] op_sel_hi:[1,0]
	v_pk_mul_f32 v[170:171], v[148:149], s[0:1] op_sel_hi:[1,0]
	v_lshl_add_u64 v[146:147], v[146:147], 0, v[0:1]
	v_cvt_pk_bf16_f32 v154, v154, v155
	v_cvt_pk_bf16_f32 v155, v156, v157
	v_cvt_pk_bf16_f32 v156, v170, v171
	v_cvt_pk_bf16_f32 v157, v158, v159
	global_store_dwordx4 v[146:147], v[154:157], off offset:256 sc1
	s_cbranch_execz .LBB0_297

.LBB0_665:
	v_lshl_or_b32 v174, s24, 8, v190
	v_lshl_add_u32 v186, s23, 8, v188
	v_ashrrev_i32_e32 v175, 31, v174
	v_readlane_b32 s4, v254, 41
	v_lshlrev_b64 v[200:201], 1, v[174:175]
	v_readlane_b32 s5, v254, 42
	v_ashrrev_i32_e32 v187, 31, v186
	v_lshlrev_b64 v[178:179], 11, v[186:187]
	v_lshl_add_u64 v[176:177], s[4:5], 0, v[200:201]
	v_lshl_add_u64 v[114:115], v[176:177], 0, v[178:179]
	global_load_dwordx4 v[192:195], v[114:115], off
	global_load_dwordx4 v[196:199], v[114:115], off offset:256
	v_or_b32_e32 v114, 16, v186
	v_ashrrev_i32_e32 v115, 31, v114
	v_lshlrev_b64 v[184:185], 11, v[114:115]
	v_lshl_add_u64 v[114:115], v[176:177], 0, v[184:185]
	global_load_dwordx4 v[134:137], v[114:115], off
	global_load_dwordx4 v[130:133], v[114:115], off offset:256
	v_or_b32_e32 v114, 32, v186
	v_ashrrev_i32_e32 v115, 31, v114
	v_lshlrev_b64 v[182:183], 11, v[114:115]
	v_lshl_add_u64 v[114:115], v[176:177], 0, v[182:183]
	global_load_dwordx4 v[126:129], v[114:115], off
	global_load_dwordx4 v[122:125], v[114:115], off offset:256
	v_or_b32_e32 v114, 48, v186
	v_ashrrev_i32_e32 v115, 31, v114
	v_lshlrev_b64 v[180:181], 11, v[114:115]
	v_lshl_add_u64 v[114:115], v[176:177], 0, v[180:181]
	global_load_dwordx4 v[118:121], v[114:115], off
	s_nop 0
	global_load_dwordx4 v[114:117], v[114:115], off offset:256
	s_waitcnt vmcnt(0)
	v_lshlrev_b32_e32 v202, 16, v192
	v_add_f32_e32 v202, v150, v202
	v_and_b32_e32 v150, 0xffff0000, v192
	v_add_f32_e32 v192, v151, v150
	v_lshlrev_b32_e32 v150, 16, v193
	v_add_f32_e32 v152, v152, v150
	v_and_b32_e32 v150, 0xffff0000, v193
	v_add_f32_e32 v153, v153, v150
	v_lshlrev_b32_e32 v150, 16, v194
	v_add_f32_e32 v193, v146, v150
	v_and_b32_e32 v146, 0xffff0000, v194
	v_add_f32_e32 v194, v147, v146
	v_lshlrev_b32_e32 v146, 16, v195
	v_add_f32_e32 v203, v148, v146
	v_and_b32_e32 v146, 0xffff0000, v195
	v_lshl_add_u64 v[150:151], s[4:5], 0, v[178:179]
	v_add_f32_e32 v195, v149, v146
	v_cvt_pk_bf16_f32 v146, v202, v192
	v_cvt_pk_bf16_f32 v147, v152, v153
	v_lshl_add_u64 v[150:151], v[150:151], 0, v[200:201]
	v_cvt_pk_bf16_f32 v148, v193, v194
	v_cvt_pk_bf16_f32 v149, v203, v195
	global_store_dwordx4 v[150:151], v[146:149], off sc1
	s_nop 1
	v_mul_f32_e32 v146, v192, v192
	v_mul_f32_e32 v147, v153, v153
	v_fmac_f32_e32 v146, v202, v202
	v_fmac_f32_e32 v147, v152, v152
	v_add_f32_e32 v146, v146, v147
	v_mul_f32_e32 v147, v194, v194
	v_fmac_f32_e32 v147, v193, v193
	v_add_f32_e32 v146, v147, v146
	v_mul_f32_e32 v147, v195, v195
	v_fmac_f32_e32 v147, v203, v203
	v_add_f32_e32 v146, v147, v146
	v_lshlrev_b32_e32 v147, 16, v196
	v_add_f32_e32 v142, v142, v147
	v_and_b32_e32 v147, 0xffff0000, v196
	v_add_f32_e32 v143, v143, v147
	v_lshlrev_b32_e32 v147, 16, v197
	v_add_f32_e32 v144, v144, v147
	v_and_b32_e32 v147, 0xffff0000, v197
	v_add_f32_e32 v145, v145, v147
	v_lshlrev_b32_e32 v147, 16, v198
	v_add_f32_e32 v147, v138, v147
	v_and_b32_e32 v138, 0xffff0000, v198
	v_add_f32_e32 v148, v139, v138
	v_lshlrev_b32_e32 v138, 16, v199
	v_add_f32_e32 v149, v140, v138
	v_and_b32_e32 v138, 0xffff0000, v199
	v_add_f32_e32 v152, v141, v138
	v_cvt_pk_bf16_f32 v138, v142, v143
	v_cvt_pk_bf16_f32 v139, v144, v145
	v_cvt_pk_bf16_f32 v140, v147, v148
	v_cvt_pk_bf16_f32 v141, v149, v152
	global_store_dwordx4 v[150:151], v[138:141], off offset:256 sc1
	s_nop 1
	v_mul_f32_e32 v138, v143, v143
	v_mul_f32_e32 v139, v145, v145
	v_fmac_f32_e32 v138, v142, v142
	v_fmac_f32_e32 v139, v144, v144
	v_add_f32_e32 v138, v138, v139
	v_mul_f32_e32 v139, v148, v148
	v_fmac_f32_e32 v139, v147, v147
	v_add_f32_e32 v138, v139, v138
	v_mul_f32_e32 v139, v152, v152
	v_fmac_f32_e32 v139, v149, v149
	v_and_b32_e32 v140, 64, v211
	v_add_f32_e32 v138, v139, v138
	v_xor_b32_e32 v139, 16, v211
	v_add_u32_e32 v141, 64, v140
	v_cmp_lt_i32_e32 vcc, v139, v141
	v_add_f32_e32 v138, v146, v138
	s_nop 0
	v_cndmask_b32_e32 v139, v211, v139, vcc
	v_lshlrev_b32_e32 v140, 2, v139
	ds_bpermute_b32 v139, v140, v138
	s_waitcnt lgkmcnt(0)
	v_add_f32_e32 v142, v138, v139
	v_xor_b32_e32 v138, 32, v211
	v_cmp_lt_i32_e32 vcc, v138, v141
	s_nop 1
	v_cndmask_b32_e32 v138, v211, v138, vcc
	v_lshlrev_b32_e32 v141, 2, v138
	ds_bpermute_b32 v143, v141, v142
	v_lshl_add_u64 v[138:139], v[186:187], 3, s[38:39]
	s_and_saveexec_b64 s[0:1], s[40:41]
	s_cbranch_execz .LBB0_667
	s_waitcnt lgkmcnt(0)
	v_add_f32_e32 v142, v142, v143
	v_mul_f32_e32 v142, 0x4b800000, v142
	v_rndne_f32_e32 v142, v142
	v_mul_f32_e32 v143, 0x2f800000, v142
	v_floor_f32_e32 v143, v143
	v_fmac_f32_e32 v142, 0xcf800000, v143
	v_cvt_u32_f32_e32 v142, v142
	v_cvt_u32_f32_e32 v143, v143
	global_atomic_add_x2 v[138:139], v[142:143], off
.LBB0_667:
	s_or_b64 exec, exec, s[0:1]
	v_lshlrev_b32_e32 v142, 16, v134
	v_and_b32_e32 v134, 0xffff0000, v134
	v_add_f32_e32 v111, v111, v134
	v_lshlrev_b32_e32 v134, 16, v135
	v_add_f32_e32 v112, v112, v134
	v_and_b32_e32 v134, 0xffff0000, v135
	v_add_f32_e32 v113, v113, v134
	v_lshlrev_b32_e32 v134, 16, v136
	v_add_f32_e32 v134, v106, v134
	v_and_b32_e32 v106, 0xffff0000, v136
	v_add_f32_e32 v135, v107, v106
	v_lshlrev_b32_e32 v106, 16, v137
	v_add_f32_e32 v136, v108, v106
	v_and_b32_e32 v106, 0xffff0000, v137
	v_add_f32_e32 v110, v110, v142
	v_add_f32_e32 v137, v109, v106
	v_cvt_pk_bf16_f32 v106, v110, v111
	v_mul_f32_e32 v111, v111, v111
	v_fmac_f32_e32 v111, v110, v110
	v_mul_f32_e32 v110, v113, v113
	v_fmac_f32_e32 v110, v112, v112
	v_add_f32_e32 v110, v111, v110
	v_mul_f32_e32 v111, v135, v135
	v_fmac_f32_e32 v111, v134, v134
	v_add_f32_e32 v110, v111, v110
	v_mul_f32_e32 v111, v137, v137
	v_fmac_f32_e32 v111, v136, v136
	v_add_f32_e32 v110, v111, v110
	v_lshlrev_b32_e32 v111, 16, v130
	v_add_f32_e32 v102, v102, v111
	v_and_b32_e32 v111, 0xffff0000, v130
	v_add_f32_e32 v103, v103, v111
	v_lshlrev_b32_e32 v111, 16, v131
	v_add_f32_e32 v111, v104, v111
	v_and_b32_e32 v104, 0xffff0000, v131
	v_cvt_pk_bf16_f32 v107, v112, v113
	v_add_f32_e32 v112, v105, v104
	v_lshlrev_b32_e32 v104, 16, v132
	v_add_f32_e32 v113, v98, v104
	v_and_b32_e32 v98, 0xffff0000, v132
	v_add_f32_e32 v130, v99, v98
	v_lshlrev_b32_e32 v98, 16, v133
	v_add_f32_e32 v131, v100, v98
	v_and_b32_e32 v98, 0xffff0000, v133
	v_add_f32_e32 v132, v101, v98
	v_mul_f32_e32 v98, v103, v103
	v_mul_f32_e32 v99, v112, v112
	v_fmac_f32_e32 v98, v102, v102
	v_fmac_f32_e32 v99, v111, v111
	v_add_f32_e32 v98, v98, v99
	v_mul_f32_e32 v99, v130, v130
	v_fmac_f32_e32 v99, v113, v113
	v_add_f32_e32 v98, v99, v98
	v_mul_f32_e32 v99, v132, v132
	v_fmac_f32_e32 v99, v131, v131
	v_add_f32_e32 v98, v99, v98
	v_add_f32_e32 v101, v110, v98
	ds_bpermute_b32 v110, v140, v101
	v_lshl_add_u64 v[98:99], s[4:5], 0, v[184:185]
	v_lshl_add_u64 v[104:105], v[174:175], 1, v[98:99]
	v_cvt_pk_bf16_f32 v108, v134, v135
	v_cvt_pk_bf16_f32 v109, v136, v137
	s_waitcnt lgkmcnt(0)
	v_add_f32_e32 v98, v101, v110
	ds_bpermute_b32 v99, v141, v98
	global_store_dwordx4 v[104:105], v[106:109], off sc1
	v_cvt_pk_bf16_f32 v100, v102, v103
	v_cvt_pk_bf16_f32 v101, v111, v112
	v_cvt_pk_bf16_f32 v102, v113, v130
	v_cvt_pk_bf16_f32 v103, v131, v132
	global_store_dwordx4 v[104:105], v[100:103], off offset:256 sc1
	s_and_saveexec_b64 s[0:1], s[40:41]
	s_cbranch_execz .LBB0_669
	s_waitcnt lgkmcnt(0)
	v_add_f32_e32 v98, v98, v99
	v_mul_f32_e32 v98, 0x4b800000, v98
	v_rndne_f32_e32 v98, v98
	v_mul_f32_e32 v99, 0x2f800000, v98
	v_floor_f32_e32 v99, v99
	v_fmac_f32_e32 v98, 0xcf800000, v99
	v_cvt_u32_f32_e32 v98, v98
	v_cvt_u32_f32_e32 v99, v99
	global_atomic_add_x2 v[138:139], v[98:99], off offset:128
.LBB0_669:
	s_or_b64 exec, exec, s[0:1]
	v_lshlrev_b32_e32 v98, 16, v126
	v_add_f32_e32 v94, v94, v98
	v_and_b32_e32 v98, 0xffff0000, v126
	v_add_f32_e32 v95, v95, v98
	v_lshlrev_b32_e32 v98, 16, v127
	v_add_f32_e32 v96, v96, v98
	v_and_b32_e32 v98, 0xffff0000, v127
	v_add_f32_e32 v97, v97, v98
	v_lshlrev_b32_e32 v98, 16, v128
	v_add_f32_e32 v98, v90, v98
	v_and_b32_e32 v90, 0xffff0000, v128
	s_waitcnt lgkmcnt(0)
	v_add_f32_e32 v99, v91, v90
	v_lshlrev_b32_e32 v90, 16, v129
	v_add_f32_e32 v100, v92, v90
	v_and_b32_e32 v90, 0xffff0000, v129
	v_add_f32_e32 v101, v93, v90
	v_cvt_pk_bf16_f32 v90, v94, v95
	v_mul_f32_e32 v95, v95, v95
	v_fmac_f32_e32 v95, v94, v94
	v_mul_f32_e32 v94, v97, v97
	v_fmac_f32_e32 v94, v96, v96
	v_add_f32_e32 v94, v95, v94
	v_mul_f32_e32 v95, v99, v99
	v_fmac_f32_e32 v95, v98, v98
	v_add_f32_e32 v94, v95, v94
	v_mul_f32_e32 v95, v101, v101
	v_fmac_f32_e32 v95, v100, v100
	v_add_f32_e32 v94, v95, v94
	v_lshlrev_b32_e32 v95, 16, v122
	v_add_f32_e32 v86, v86, v95
	v_and_b32_e32 v95, 0xffff0000, v122
	v_add_f32_e32 v87, v87, v95
	v_lshlrev_b32_e32 v95, 16, v123
	v_add_f32_e32 v95, v88, v95
	v_and_b32_e32 v88, 0xffff0000, v123
	v_cvt_pk_bf16_f32 v91, v96, v97
	v_add_f32_e32 v96, v89, v88
	v_lshlrev_b32_e32 v88, 16, v124
	v_add_f32_e32 v97, v82, v88
	v_and_b32_e32 v82, 0xffff0000, v124
	v_cvt_pk_bf16_f32 v92, v98, v99
	v_add_f32_e32 v98, v83, v82
	v_lshlrev_b32_e32 v82, 16, v125
	v_add_f32_e32 v99, v84, v82
	v_and_b32_e32 v82, 0xffff0000, v125
	v_cvt_pk_bf16_f32 v93, v100, v101
	v_add_f32_e32 v100, v85, v82
	v_mul_f32_e32 v82, v87, v87
	v_mul_f32_e32 v83, v96, v96
	v_fmac_f32_e32 v82, v86, v86
	v_fmac_f32_e32 v83, v95, v95
	v_add_f32_e32 v82, v82, v83
	v_mul_f32_e32 v83, v98, v98
	v_fmac_f32_e32 v83, v97, v97
	v_add_f32_e32 v82, v83, v82
	v_mul_f32_e32 v83, v100, v100
	v_fmac_f32_e32 v83, v99, v99
	v_add_f32_e32 v82, v83, v82
	v_add_f32_e32 v85, v94, v82
	ds_bpermute_b32 v94, v140, v85
	v_lshl_add_u64 v[82:83], s[4:5], 0, v[182:183]
	v_lshl_add_u64 v[88:89], v[174:175], 1, v[82:83]
	global_store_dwordx4 v[88:89], v[90:93], off sc1
	v_cvt_pk_bf16_f32 v84, v86, v87
	s_waitcnt lgkmcnt(0)
	v_add_f32_e32 v82, v85, v94
	ds_bpermute_b32 v83, v141, v82
	v_cvt_pk_bf16_f32 v85, v95, v96
	v_cvt_pk_bf16_f32 v86, v97, v98
	v_cvt_pk_bf16_f32 v87, v99, v100
	global_store_dwordx4 v[88:89], v[84:87], off offset:256 sc1
	s_and_saveexec_b64 s[0:1], s[40:41]
	s_cbranch_execz .LBB0_671
	s_waitcnt lgkmcnt(0)
	v_add_f32_e32 v82, v82, v83
	v_mul_f32_e32 v82, 0x4b800000, v82
	v_rndne_f32_e32 v82, v82
	v_mul_f32_e32 v83, 0x2f800000, v82
	v_floor_f32_e32 v83, v83
	v_fmac_f32_e32 v82, 0xcf800000, v83
	v_cvt_u32_f32_e32 v82, v82
	v_cvt_u32_f32_e32 v83, v83
	global_atomic_add_x2 v[138:139], v[82:83], off offset:256
.LBB0_671:
	s_or_b64 exec, exec, s[0:1]
	v_lshlrev_b32_e32 v82, 16, v118
	v_add_f32_e32 v78, v78, v82
	v_and_b32_e32 v82, 0xffff0000, v118
	v_add_f32_e32 v79, v79, v82
	v_lshlrev_b32_e32 v82, 16, v119
	v_add_f32_e32 v80, v80, v82
	v_and_b32_e32 v82, 0xffff0000, v119
	v_add_f32_e32 v81, v81, v82
	v_lshlrev_b32_e32 v82, 16, v120
	v_add_f32_e32 v82, v74, v82
	v_and_b32_e32 v74, 0xffff0000, v120
	s_waitcnt lgkmcnt(0)
	v_add_f32_e32 v83, v75, v74
	v_lshlrev_b32_e32 v74, 16, v121
	v_add_f32_e32 v84, v76, v74
	v_and_b32_e32 v74, 0xffff0000, v121
	v_add_f32_e32 v85, v77, v74
	v_cvt_pk_bf16_f32 v74, v78, v79
	v_mul_f32_e32 v79, v79, v79
	v_fmac_f32_e32 v79, v78, v78
	v_mul_f32_e32 v78, v81, v81
	v_fmac_f32_e32 v78, v80, v80
	v_add_f32_e32 v78, v79, v78
	v_mul_f32_e32 v79, v83, v83
	v_fmac_f32_e32 v79, v82, v82
	v_add_f32_e32 v78, v79, v78
	v_mul_f32_e32 v79, v85, v85
	v_fmac_f32_e32 v79, v84, v84
	v_add_f32_e32 v78, v79, v78
	v_lshlrev_b32_e32 v79, 16, v114
	v_add_f32_e32 v70, v70, v79
	v_and_b32_e32 v79, 0xffff0000, v114
	v_add_f32_e32 v71, v71, v79
	v_lshlrev_b32_e32 v79, 16, v115
	v_add_f32_e32 v79, v72, v79
	v_and_b32_e32 v72, 0xffff0000, v115
	v_cvt_pk_bf16_f32 v75, v80, v81
	v_add_f32_e32 v80, v73, v72
	v_lshlrev_b32_e32 v72, 16, v116
	v_add_f32_e32 v81, v66, v72
	v_and_b32_e32 v66, 0xffff0000, v116
	v_cvt_pk_bf16_f32 v76, v82, v83
	v_add_f32_e32 v82, v67, v66
	v_lshlrev_b32_e32 v66, 16, v117
	v_add_f32_e32 v83, v68, v66
	v_and_b32_e32 v66, 0xffff0000, v117
	v_cvt_pk_bf16_f32 v77, v84, v85
	v_add_f32_e32 v84, v69, v66
	v_mul_f32_e32 v66, v71, v71
	v_mul_f32_e32 v67, v80, v80
	v_fmac_f32_e32 v66, v70, v70
	v_fmac_f32_e32 v67, v79, v79
	v_add_f32_e32 v66, v66, v67
	v_mul_f32_e32 v67, v82, v82
	v_fmac_f32_e32 v67, v81, v81
	v_add_f32_e32 v66, v67, v66
	v_mul_f32_e32 v67, v84, v84
	v_fmac_f32_e32 v67, v83, v83
	v_add_f32_e32 v66, v67, v66
	v_add_f32_e32 v69, v78, v66
	ds_bpermute_b32 v78, v140, v69
	v_lshl_add_u64 v[66:67], s[4:5], 0, v[180:181]
	v_lshl_add_u64 v[72:73], v[174:175], 1, v[66:67]
	global_store_dwordx4 v[72:73], v[74:77], off sc1
	v_cvt_pk_bf16_f32 v68, v70, v71
	s_waitcnt lgkmcnt(0)
	v_add_f32_e32 v66, v69, v78
	ds_bpermute_b32 v67, v141, v66
	v_cvt_pk_bf16_f32 v69, v79, v80
	v_cvt_pk_bf16_f32 v70, v81, v82
	v_cvt_pk_bf16_f32 v71, v83, v84
	global_store_dwordx4 v[72:73], v[68:71], off offset:256 sc1
	s_and_saveexec_b64 s[0:1], s[40:41]
	s_cbranch_execz .LBB0_673
	s_waitcnt lgkmcnt(0)
	v_add_f32_e32 v66, v66, v67
	v_mul_f32_e32 v66, 0x4b800000, v66
	v_rndne_f32_e32 v66, v66
	v_mul_f32_e32 v67, 0x2f800000, v66
	v_floor_f32_e32 v67, v67
	v_fmac_f32_e32 v66, 0xcf800000, v67
	v_cvt_u32_f32_e32 v66, v66
	v_cvt_u32_f32_e32 v67, v67
	global_atomic_add_x2 v[138:139], v[66:67], off offset:384
.LBB0_673:
	s_or_b64 exec, exec, s[0:1]
	v_lshl_add_u64 v[104:105], v[178:179], 0, s[46:47]
	s_waitcnt lgkmcnt(0)
	v_lshl_add_u64 v[66:67], v[176:177], 0, v[104:105]
	global_load_dwordx4 v[100:103], v[66:67], off
	global_load_dwordx4 v[90:93], v[66:67], off offset:256
	s_mov_b64 s[0:1], 0x48000
	v_lshl_add_u64 v[98:99], v[178:179], 0, s[0:1]
	s_mov_b64 s[0:1], 0x50000
	v_lshl_add_u64 v[66:67], v[176:177], 0, v[98:99]
	v_lshl_add_u64 v[96:97], v[178:179], 0, s[0:1]
	s_mov_b64 s[0:1], 0x58000
	global_load_dwordx4 v[86:89], v[66:67], off
	global_load_dwordx4 v[82:85], v[66:67], off offset:256
	v_lshl_add_u64 v[66:67], v[176:177], 0, v[96:97]
	v_lshl_add_u64 v[94:95], v[178:179], 0, s[0:1]
	global_load_dwordx4 v[78:81], v[66:67], off
	global_load_dwordx4 v[74:77], v[66:67], off offset:256
	v_lshl_add_u64 v[66:67], v[176:177], 0, v[94:95]
	global_load_dwordx4 v[70:73], v[66:67], off
	s_nop 0
	global_load_dwordx4 v[66:69], v[66:67], off offset:256
	s_waitcnt vmcnt(7)
	v_lshlrev_b32_e32 v106, 16, v100
	v_add_f32_e32 v106, v62, v106
	v_and_b32_e32 v62, 0xffff0000, v100
	v_add_f32_e32 v100, v63, v62
	v_lshlrev_b32_e32 v62, 16, v101
	v_add_f32_e32 v64, v64, v62
	v_and_b32_e32 v62, 0xffff0000, v101
	v_add_f32_e32 v65, v65, v62
	v_lshlrev_b32_e32 v62, 16, v102
	v_add_f32_e32 v101, v58, v62
	v_and_b32_e32 v58, 0xffff0000, v102
	v_add_f32_e32 v102, v59, v58
	v_lshlrev_b32_e32 v58, 16, v103
	v_add_f32_e32 v107, v60, v58
	v_and_b32_e32 v58, 0xffff0000, v103
	v_lshl_add_u64 v[62:63], s[4:5], 0, v[104:105]
	v_add_f32_e32 v103, v61, v58
	v_cvt_pk_bf16_f32 v58, v106, v100
	v_cvt_pk_bf16_f32 v59, v64, v65
	v_lshl_add_u64 v[62:63], v[174:175], 1, v[62:63]
	v_cvt_pk_bf16_f32 v60, v101, v102
	v_cvt_pk_bf16_f32 v61, v107, v103
	global_store_dwordx4 v[62:63], v[58:61], off sc1
	s_nop 1
	v_mul_f32_e32 v58, v100, v100
	v_mul_f32_e32 v59, v65, v65
	v_fmac_f32_e32 v58, v106, v106
	v_fmac_f32_e32 v59, v64, v64
	v_add_f32_e32 v58, v58, v59
	v_mul_f32_e32 v59, v102, v102
	v_fmac_f32_e32 v59, v101, v101
	v_add_f32_e32 v58, v59, v58
	v_mul_f32_e32 v59, v103, v103
	v_fmac_f32_e32 v59, v107, v107
	v_add_f32_e32 v58, v59, v58
	s_waitcnt vmcnt(7)
	v_lshlrev_b32_e32 v59, 16, v90
	v_add_f32_e32 v54, v54, v59
	v_and_b32_e32 v59, 0xffff0000, v90
	v_add_f32_e32 v55, v55, v59
	v_lshlrev_b32_e32 v59, 16, v91
	v_add_f32_e32 v56, v56, v59
	v_and_b32_e32 v59, 0xffff0000, v91
	v_add_f32_e32 v57, v57, v59
	v_lshlrev_b32_e32 v59, 16, v92
	v_add_f32_e32 v59, v50, v59
	v_and_b32_e32 v50, 0xffff0000, v92
	v_add_f32_e32 v60, v51, v50
	v_lshlrev_b32_e32 v50, 16, v93
	v_add_f32_e32 v61, v52, v50
	v_and_b32_e32 v50, 0xffff0000, v93
	v_add_f32_e32 v64, v53, v50
	v_cvt_pk_bf16_f32 v50, v54, v55
	v_cvt_pk_bf16_f32 v51, v56, v57
	v_cvt_pk_bf16_f32 v52, v59, v60
	v_cvt_pk_bf16_f32 v53, v61, v64
	global_store_dwordx4 v[62:63], v[50:53], off offset:256 sc1
	s_nop 1
	v_mul_f32_e32 v50, v55, v55
	v_mul_f32_e32 v51, v57, v57
	v_fmac_f32_e32 v50, v54, v54
	v_fmac_f32_e32 v51, v56, v56
	v_add_f32_e32 v50, v50, v51
	v_mul_f32_e32 v51, v60, v60
	v_fmac_f32_e32 v51, v59, v59
	v_add_f32_e32 v50, v51, v50
	v_mul_f32_e32 v51, v64, v64
	v_fmac_f32_e32 v51, v61, v61
	v_add_f32_e32 v50, v51, v50
	v_add_f32_e32 v50, v58, v50
	ds_bpermute_b32 v51, v140, v50
	s_waitcnt lgkmcnt(0)
	v_add_f32_e32 v50, v50, v51
	ds_bpermute_b32 v51, v141, v50
	s_and_saveexec_b64 s[0:1], s[40:41]
	s_cbranch_execz .LBB0_675
	s_waitcnt lgkmcnt(0)
	v_add_f32_e32 v50, v50, v51
	v_mul_f32_e32 v50, 0x4b800000, v50
	v_rndne_f32_e32 v50, v50
	v_mul_f32_e32 v51, 0x2f800000, v50
	v_floor_f32_e32 v51, v51
	v_fmac_f32_e32 v50, 0xcf800000, v51
	v_cvt_u32_f32_e32 v50, v50
	v_cvt_u32_f32_e32 v51, v51
	global_atomic_add_x2 v[138:139], v[50:51], off offset:1024
.LBB0_675:
	s_or_b64 exec, exec, s[0:1]
	s_waitcnt vmcnt(7)
	v_lshlrev_b32_e32 v50, 16, v86
	v_add_f32_e32 v46, v46, v50
	v_and_b32_e32 v50, 0xffff0000, v86
	v_add_f32_e32 v47, v47, v50
	v_lshlrev_b32_e32 v50, 16, v87
	v_add_f32_e32 v48, v48, v50
	v_and_b32_e32 v50, 0xffff0000, v87
	v_add_f32_e32 v49, v49, v50
	v_lshlrev_b32_e32 v50, 16, v88
	v_add_f32_e32 v50, v42, v50
	v_and_b32_e32 v42, 0xffff0000, v88
	s_waitcnt lgkmcnt(0)
	v_add_f32_e32 v51, v43, v42
	v_lshlrev_b32_e32 v42, 16, v89
	v_add_f32_e32 v52, v44, v42
	v_and_b32_e32 v42, 0xffff0000, v89
	v_add_f32_e32 v53, v45, v42
	v_cvt_pk_bf16_f32 v42, v46, v47
	v_mul_f32_e32 v47, v47, v47
	v_fmac_f32_e32 v47, v46, v46
	v_mul_f32_e32 v46, v49, v49
	v_fmac_f32_e32 v46, v48, v48
	v_add_f32_e32 v46, v47, v46
	v_mul_f32_e32 v47, v51, v51
	v_fmac_f32_e32 v47, v50, v50
	v_add_f32_e32 v46, v47, v46
	v_mul_f32_e32 v47, v53, v53
	v_fmac_f32_e32 v47, v52, v52
	v_add_f32_e32 v46, v47, v46
	s_waitcnt vmcnt(6)
	v_lshlrev_b32_e32 v47, 16, v82
	v_add_f32_e32 v38, v38, v47
	v_and_b32_e32 v47, 0xffff0000, v82
	v_add_f32_e32 v39, v39, v47
	v_lshlrev_b32_e32 v47, 16, v83
	v_add_f32_e32 v47, v40, v47
	v_and_b32_e32 v40, 0xffff0000, v83
	v_cvt_pk_bf16_f32 v43, v48, v49
	v_add_f32_e32 v48, v41, v40
	v_lshlrev_b32_e32 v40, 16, v84
	v_add_f32_e32 v49, v34, v40
	v_and_b32_e32 v34, 0xffff0000, v84
	v_cvt_pk_bf16_f32 v44, v50, v51
	v_add_f32_e32 v50, v35, v34
	v_lshlrev_b32_e32 v34, 16, v85
	v_add_f32_e32 v51, v36, v34
	v_and_b32_e32 v34, 0xffff0000, v85
	v_cvt_pk_bf16_f32 v45, v52, v53
	v_add_f32_e32 v52, v37, v34
	v_mul_f32_e32 v34, v39, v39
	v_mul_f32_e32 v35, v48, v48
	v_fmac_f32_e32 v34, v38, v38
	v_fmac_f32_e32 v35, v47, v47
	v_add_f32_e32 v34, v34, v35
	v_mul_f32_e32 v35, v50, v50
	v_fmac_f32_e32 v35, v49, v49
	v_add_f32_e32 v34, v35, v34
	v_mul_f32_e32 v35, v52, v52
	v_fmac_f32_e32 v35, v51, v51
	v_add_f32_e32 v34, v35, v34
	v_add_f32_e32 v37, v46, v34
	ds_bpermute_b32 v46, v140, v37
	v_lshl_add_u64 v[34:35], s[4:5], 0, v[98:99]
	v_lshl_add_u64 v[40:41], v[174:175], 1, v[34:35]
	global_store_dwordx4 v[40:41], v[42:45], off sc1
	v_cvt_pk_bf16_f32 v36, v38, v39
	s_waitcnt lgkmcnt(0)
	v_add_f32_e32 v34, v37, v46
	ds_bpermute_b32 v35, v141, v34
	v_cvt_pk_bf16_f32 v37, v47, v48
	v_cvt_pk_bf16_f32 v38, v49, v50
	v_cvt_pk_bf16_f32 v39, v51, v52
	global_store_dwordx4 v[40:41], v[36:39], off offset:256 sc1
	s_and_saveexec_b64 s[0:1], s[40:41]
	s_cbranch_execz .LBB0_677
	s_waitcnt lgkmcnt(0)
	v_add_f32_e32 v34, v34, v35
	v_mul_f32_e32 v34, 0x4b800000, v34
	v_rndne_f32_e32 v34, v34
	v_mul_f32_e32 v35, 0x2f800000, v34
	v_floor_f32_e32 v35, v35
	v_fmac_f32_e32 v34, 0xcf800000, v35
	v_cvt_u32_f32_e32 v34, v34
	v_cvt_u32_f32_e32 v35, v35
	global_atomic_add_x2 v[138:139], v[34:35], off offset:1152
.LBB0_677:
	s_or_b64 exec, exec, s[0:1]
	s_waitcnt vmcnt(7)
	v_lshlrev_b32_e32 v34, 16, v78
	v_add_f32_e32 v30, v30, v34
	v_and_b32_e32 v34, 0xffff0000, v78
	v_add_f32_e32 v31, v31, v34
	v_lshlrev_b32_e32 v34, 16, v79
	v_add_f32_e32 v32, v32, v34
	v_and_b32_e32 v34, 0xffff0000, v79
	v_add_f32_e32 v33, v33, v34
	v_lshlrev_b32_e32 v34, 16, v80
	v_add_f32_e32 v34, v26, v34
	v_and_b32_e32 v26, 0xffff0000, v80
	s_waitcnt lgkmcnt(0)
	v_add_f32_e32 v35, v27, v26
	v_lshlrev_b32_e32 v26, 16, v81
	v_add_f32_e32 v36, v28, v26
	v_and_b32_e32 v26, 0xffff0000, v81
	v_add_f32_e32 v37, v29, v26
	v_cvt_pk_bf16_f32 v26, v30, v31
	v_mul_f32_e32 v31, v31, v31
	v_fmac_f32_e32 v31, v30, v30
	v_mul_f32_e32 v30, v33, v33
	v_fmac_f32_e32 v30, v32, v32
	v_add_f32_e32 v30, v31, v30
	v_mul_f32_e32 v31, v35, v35
	v_fmac_f32_e32 v31, v34, v34
	v_add_f32_e32 v30, v31, v30
	v_mul_f32_e32 v31, v37, v37
	v_fmac_f32_e32 v31, v36, v36
	v_add_f32_e32 v30, v31, v30
	s_waitcnt vmcnt(6)
	v_lshlrev_b32_e32 v31, 16, v74
	v_add_f32_e32 v22, v22, v31
	v_and_b32_e32 v31, 0xffff0000, v74
	v_add_f32_e32 v23, v23, v31
	v_lshlrev_b32_e32 v31, 16, v75
	v_add_f32_e32 v31, v24, v31
	v_and_b32_e32 v24, 0xffff0000, v75
	v_cvt_pk_bf16_f32 v27, v32, v33
	v_add_f32_e32 v32, v25, v24
	v_lshlrev_b32_e32 v24, 16, v76
	v_add_f32_e32 v33, v18, v24
	v_and_b32_e32 v18, 0xffff0000, v76
	v_cvt_pk_bf16_f32 v28, v34, v35
	v_add_f32_e32 v34, v19, v18
	v_lshlrev_b32_e32 v18, 16, v77
	v_add_f32_e32 v35, v20, v18
	v_and_b32_e32 v18, 0xffff0000, v77
	v_cvt_pk_bf16_f32 v29, v36, v37
	v_add_f32_e32 v36, v21, v18
	v_mul_f32_e32 v18, v23, v23
	v_mul_f32_e32 v19, v32, v32
	v_fmac_f32_e32 v18, v22, v22
	v_fmac_f32_e32 v19, v31, v31
	v_add_f32_e32 v18, v18, v19
	v_mul_f32_e32 v19, v34, v34
	v_fmac_f32_e32 v19, v33, v33
	v_add_f32_e32 v18, v19, v18
	v_mul_f32_e32 v19, v36, v36
	v_fmac_f32_e32 v19, v35, v35
	v_add_f32_e32 v18, v19, v18
	v_add_f32_e32 v21, v30, v18
	ds_bpermute_b32 v30, v140, v21
	v_lshl_add_u64 v[18:19], s[4:5], 0, v[96:97]
	v_lshl_add_u64 v[24:25], v[174:175], 1, v[18:19]
	global_store_dwordx4 v[24:25], v[26:29], off sc1
	v_cvt_pk_bf16_f32 v20, v22, v23
	s_waitcnt lgkmcnt(0)
	v_add_f32_e32 v18, v21, v30
	ds_bpermute_b32 v19, v141, v18
	v_cvt_pk_bf16_f32 v21, v31, v32
	v_cvt_pk_bf16_f32 v22, v33, v34
	v_cvt_pk_bf16_f32 v23, v35, v36
	global_store_dwordx4 v[24:25], v[20:23], off offset:256 sc1
	s_and_saveexec_b64 s[0:1], s[40:41]
	s_cbranch_execz .LBB0_679
	s_waitcnt lgkmcnt(0)
	v_add_f32_e32 v18, v18, v19
	v_mul_f32_e32 v18, 0x4b800000, v18
	v_rndne_f32_e32 v18, v18
	v_mul_f32_e32 v19, 0x2f800000, v18
	v_floor_f32_e32 v19, v19
	v_fmac_f32_e32 v18, 0xcf800000, v19
	v_cvt_u32_f32_e32 v18, v18
	v_cvt_u32_f32_e32 v19, v19
	global_atomic_add_x2 v[138:139], v[18:19], off offset:1280
.LBB0_679:
	s_or_b64 exec, exec, s[0:1]
	s_waitcnt vmcnt(7)
	v_lshlrev_b32_e32 v18, 16, v70
	v_add_f32_e32 v14, v14, v18
	v_and_b32_e32 v18, 0xffff0000, v70
	v_add_f32_e32 v15, v15, v18
	v_lshlrev_b32_e32 v18, 16, v71
	v_add_f32_e32 v16, v16, v18
	v_and_b32_e32 v18, 0xffff0000, v71
	v_add_f32_e32 v17, v17, v18
	v_lshlrev_b32_e32 v18, 16, v72
	v_add_f32_e32 v18, v10, v18
	v_and_b32_e32 v10, 0xffff0000, v72
	s_waitcnt lgkmcnt(0)
	v_add_f32_e32 v19, v11, v10
	v_lshlrev_b32_e32 v10, 16, v73
	v_add_f32_e32 v20, v12, v10
	v_and_b32_e32 v10, 0xffff0000, v73
	v_add_f32_e32 v21, v13, v10
	v_cvt_pk_bf16_f32 v10, v14, v15
	v_mul_f32_e32 v15, v15, v15
	v_fmac_f32_e32 v15, v14, v14
	v_mul_f32_e32 v14, v17, v17
	v_fmac_f32_e32 v14, v16, v16
	v_add_f32_e32 v14, v15, v14
	v_mul_f32_e32 v15, v19, v19
	v_fmac_f32_e32 v15, v18, v18
	v_add_f32_e32 v14, v15, v14
	v_mul_f32_e32 v15, v21, v21
	v_fmac_f32_e32 v15, v20, v20
	v_add_f32_e32 v14, v15, v14
	s_waitcnt vmcnt(6)
	v_lshlrev_b32_e32 v15, 16, v66
	v_add_f32_e32 v6, v6, v15
	v_and_b32_e32 v15, 0xffff0000, v66
	v_add_f32_e32 v7, v7, v15
	v_lshlrev_b32_e32 v15, 16, v67
	v_add_f32_e32 v15, v8, v15
	v_and_b32_e32 v8, 0xffff0000, v67
	v_cvt_pk_bf16_f32 v11, v16, v17
	v_add_f32_e32 v16, v9, v8
	v_lshlrev_b32_e32 v8, 16, v68
	v_add_f32_e32 v17, v2, v8
	v_and_b32_e32 v2, 0xffff0000, v68
	v_cvt_pk_bf16_f32 v12, v18, v19
	v_add_f32_e32 v18, v3, v2
	v_lshlrev_b32_e32 v2, 16, v69
	v_add_f32_e32 v19, v4, v2
	v_and_b32_e32 v2, 0xffff0000, v69
	v_cvt_pk_bf16_f32 v13, v20, v21
	v_add_f32_e32 v20, v5, v2
	v_mul_f32_e32 v2, v7, v7
	v_mul_f32_e32 v3, v16, v16
	v_fmac_f32_e32 v2, v6, v6
	v_fmac_f32_e32 v3, v15, v15
	v_add_f32_e32 v2, v2, v3
	v_mul_f32_e32 v3, v18, v18
	v_fmac_f32_e32 v3, v17, v17
	v_add_f32_e32 v2, v3, v2
	v_mul_f32_e32 v3, v20, v20
	v_fmac_f32_e32 v3, v19, v19
	v_add_f32_e32 v2, v3, v2
	v_add_f32_e32 v5, v14, v2
	ds_bpermute_b32 v14, v140, v5
	v_lshl_add_u64 v[2:3], s[4:5], 0, v[94:95]
	v_lshl_add_u64 v[8:9], v[174:175], 1, v[2:3]
	global_store_dwordx4 v[8:9], v[10:13], off sc1
	v_cvt_pk_bf16_f32 v4, v6, v7
	s_waitcnt lgkmcnt(0)
	v_add_f32_e32 v2, v5, v14
	ds_bpermute_b32 v3, v141, v2
	v_cvt_pk_bf16_f32 v5, v15, v16
	v_cvt_pk_bf16_f32 v6, v17, v18
	v_cvt_pk_bf16_f32 v7, v19, v20
	global_store_dwordx4 v[8:9], v[4:7], off offset:256 sc1
	s_and_saveexec_b64 s[0:1], s[40:41]
	s_cbranch_execz .LBB0_681
	s_waitcnt lgkmcnt(0)
	v_add_f32_e32 v2, v2, v3
	v_mul_f32_e32 v2, 0x4b800000, v2
	v_rndne_f32_e32 v2, v2
	v_mul_f32_e32 v3, 0x2f800000, v2
	v_floor_f32_e32 v3, v3
	v_fmac_f32_e32 v2, 0xcf800000, v3
	v_cvt_u32_f32_e32 v2, v2
	v_cvt_u32_f32_e32 v3, v3
	global_atomic_add_x2 v[138:139], v[2:3], off offset:1408

.LBB0_703:
	v_mov_b32_e32 v122, s28
	v_mov_b32_e32 v123, s25
	v_lshl_add_u64 v[122:123], v[140:141], 1, v[122:123]
	v_mad_i64_i32 v[172:173], s[28:29], s24, v142, 0
	s_andn2_b64 vcc, exec, s[6:7]
	v_lshl_add_u64 v[172:173], v[172:173], 1, v[122:123]
	s_cbranch_vccnz .LBB0_705
	v_cvt_pk_bf16_f32 v178, v170, v171
	v_cvt_pk_bf16_f32 v179, v128, v129
	v_cvt_pk_bf16_f32 v180, v126, v127
	v_cvt_pk_bf16_f32 v181, v124, v125
	global_store_dwordx4 v[172:173], v[178:181], off sc1

.LBB0_707:
	s_andn2_b64 vcc, exec, s[0:1]
	s_cbranch_vccnz .LBB0_709
	v_cvt_pk_bf16_f32 v118, v118, v119
	v_cvt_pk_bf16_f32 v119, v120, v121
	v_cvt_pk_bf16_f32 v120, v114, v115
	v_cvt_pk_bf16_f32 v121, v116, v117
	global_store_dwordx4 v[172:173], v[118:121], off offset:256 sc1

.LBB0_711:
	v_mad_i64_i32 v[106:107], s[6:7], s24, v118, 0
	s_andn2_b64 vcc, exec, s[0:1]
	v_lshl_add_u64 v[106:107], v[106:107], 1, v[122:123]
	s_cbranch_vccnz .LBB0_713
	v_cvt_pk_bf16_f32 v124, v116, v117
	v_cvt_pk_bf16_f32 v125, v112, v113
	v_cvt_pk_bf16_f32 v126, v110, v111
	v_cvt_pk_bf16_f32 v127, v108, v109
	global_store_dwordx4 v[106:107], v[124:127], off sc1

.LBB0_715:
	s_andn2_b64 vcc, exec, s[0:1]
	s_cbranch_vccnz .LBB0_717
	v_cvt_pk_bf16_f32 v102, v102, v103
	v_cvt_pk_bf16_f32 v103, v104, v105
	v_cvt_pk_bf16_f32 v104, v98, v99
	v_cvt_pk_bf16_f32 v105, v100, v101
	global_store_dwordx4 v[106:107], v[102:105], off offset:256 sc1

.LBB0_719:
	v_mad_i64_i32 v[90:91], s[6:7], s24, v102, 0
	s_andn2_b64 vcc, exec, s[0:1]
	v_lshl_add_u64 v[90:91], v[90:91], 1, v[122:123]
	s_cbranch_vccnz .LBB0_721
	v_cvt_pk_bf16_f32 v104, v100, v101
	v_cvt_pk_bf16_f32 v105, v96, v97
	v_cvt_pk_bf16_f32 v106, v94, v95
	v_cvt_pk_bf16_f32 v107, v92, v93
	global_store_dwordx4 v[90:91], v[104:107], off sc1

.LBB0_723:
	s_andn2_b64 vcc, exec, s[0:1]
	s_cbranch_vccnz .LBB0_725
	v_cvt_pk_bf16_f32 v86, v86, v87
	v_cvt_pk_bf16_f32 v87, v88, v89
	v_cvt_pk_bf16_f32 v88, v82, v83
	v_cvt_pk_bf16_f32 v89, v84, v85
	global_store_dwordx4 v[90:91], v[86:89], off offset:256 sc1

.LBB0_727:
	v_mad_i64_i32 v[74:75], s[6:7], s24, v86, 0
	s_andn2_b64 vcc, exec, s[0:1]
	v_lshl_add_u64 v[74:75], v[74:75], 1, v[122:123]
	s_cbranch_vccnz .LBB0_729
	v_cvt_pk_bf16_f32 v88, v84, v85
	v_cvt_pk_bf16_f32 v89, v80, v81
	v_cvt_pk_bf16_f32 v90, v78, v79
	v_cvt_pk_bf16_f32 v91, v76, v77
	global_store_dwordx4 v[74:75], v[88:91], off sc1

.LBB0_731:
	s_andn2_b64 vcc, exec, s[0:1]
	s_cbranch_vccnz .LBB0_733
	v_cvt_pk_bf16_f32 v70, v70, v71
	v_cvt_pk_bf16_f32 v71, v72, v73
	v_cvt_pk_bf16_f32 v72, v66, v67
	v_cvt_pk_bf16_f32 v73, v68, v69
	global_store_dwordx4 v[74:75], v[70:73], off offset:256 sc1

.LBB0_735:
	v_mad_i64_i32 v[58:59], s[6:7], s24, v70, 0
	s_andn2_b64 vcc, exec, s[0:1]
	v_lshl_add_u64 v[58:59], v[58:59], 1, v[122:123]
	s_cbranch_vccnz .LBB0_737
	v_cvt_pk_bf16_f32 v72, v68, v69
	v_cvt_pk_bf16_f32 v73, v64, v65
	v_cvt_pk_bf16_f32 v74, v62, v63
	v_cvt_pk_bf16_f32 v75, v60, v61
	global_store_dwordx4 v[58:59], v[72:75], off sc1

.LBB0_739:
	s_andn2_b64 vcc, exec, s[0:1]
	s_cbranch_vccnz .LBB0_741
	v_cvt_pk_bf16_f32 v54, v54, v55
	v_cvt_pk_bf16_f32 v55, v56, v57
	v_cvt_pk_bf16_f32 v56, v50, v51
	v_cvt_pk_bf16_f32 v57, v52, v53
	global_store_dwordx4 v[58:59], v[54:57], off offset:256 sc1

.LBB0_743:
	v_mad_i64_i32 v[42:43], s[6:7], s24, v54, 0
	s_andn2_b64 vcc, exec, s[0:1]
	v_lshl_add_u64 v[42:43], v[42:43], 1, v[122:123]
	s_cbranch_vccnz .LBB0_745
	v_cvt_pk_bf16_f32 v56, v52, v53
	v_cvt_pk_bf16_f32 v57, v48, v49
	v_cvt_pk_bf16_f32 v58, v46, v47
	v_cvt_pk_bf16_f32 v59, v44, v45
	global_store_dwordx4 v[42:43], v[56:59], off sc1

.LBB0_747:
	s_andn2_b64 vcc, exec, s[0:1]
	s_cbranch_vccnz .LBB0_749
	v_cvt_pk_bf16_f32 v38, v38, v39
	v_cvt_pk_bf16_f32 v39, v40, v41
	v_cvt_pk_bf16_f32 v40, v34, v35
	v_cvt_pk_bf16_f32 v41, v36, v37
	global_store_dwordx4 v[42:43], v[38:41], off offset:256 sc1

.LBB0_751:
	v_mad_i64_i32 v[26:27], s[6:7], s24, v38, 0
	s_andn2_b64 vcc, exec, s[0:1]
	v_lshl_add_u64 v[26:27], v[26:27], 1, v[122:123]
	s_cbranch_vccnz .LBB0_753
	v_cvt_pk_bf16_f32 v40, v36, v37
	v_cvt_pk_bf16_f32 v41, v32, v33
	v_cvt_pk_bf16_f32 v42, v30, v31
	v_cvt_pk_bf16_f32 v43, v28, v29
	global_store_dwordx4 v[26:27], v[40:43], off sc1

.LBB0_755:
	s_andn2_b64 vcc, exec, s[0:1]
	s_cbranch_vccnz .LBB0_757
	v_cvt_pk_bf16_f32 v22, v22, v23
	v_cvt_pk_bf16_f32 v23, v24, v25
	v_cvt_pk_bf16_f32 v24, v18, v19
	v_cvt_pk_bf16_f32 v25, v20, v21
	global_store_dwordx4 v[26:27], v[22:25], off offset:256 sc1

.LBB0_759:
	v_mad_i64_i32 v[10:11], s[6:7], s24, v22, 0
	s_andn2_b64 vcc, exec, s[0:1]
	v_lshl_add_u64 v[10:11], v[10:11], 1, v[122:123]
	s_cbranch_vccnz .LBB0_761
	v_cvt_pk_bf16_f32 v24, v20, v21
	v_cvt_pk_bf16_f32 v25, v16, v17
	v_cvt_pk_bf16_f32 v26, v14, v15
	v_cvt_pk_bf16_f32 v27, v12, v13
	global_store_dwordx4 v[10:11], v[24:27], off sc1

.LBB0_765:
	v_cvt_pk_bf16_f32 v6, v6, v7
	v_cvt_pk_bf16_f32 v7, v8, v9
	v_cvt_pk_bf16_f32 v8, v2, v3
	v_cvt_pk_bf16_f32 v9, v4, v5
	global_store_dwordx4 v[10:11], v[6:9], off offset:256 sc1
	s_andn2_b64 vcc, exec, s[40:41]
	s_mov_b64 s[0:1], -1
	s_cbranch_vccnz .LBB0_694

.LBB0_781:
	v_lshl_or_b32 v174, s22, 8, v180
	v_ashrrev_i32_e32 v175, 31, v174
	v_lshl_add_u64 v[142:143], v[174:175], 3, s[2:3]
	global_load_dwordx4 v[130:133], v[142:143], off offset:48
	global_load_dwordx4 v[134:137], v[142:143], off offset:32
	global_load_dwordx4 v[138:141], v[142:143], off offset:16
	global_load_dwordx4 v[156:159], v[142:143], off
	s_mov_b32 s6, 0x33800000
	s_mov_b32 s0, 0x358637bd
	v_mov_b64_e32 v[176:177], s[0:1]
	s_mov_b32 s22, 0x3a800000
	s_mov_b32 s0, 0x800000
	s_mov_b32 s24, 0x45800000
	s_waitcnt vmcnt(0)
	v_ffbh_u32_e32 v144, v159
	v_min_u32_e32 v170, 32, v144
	v_lshlrev_b64 v[144:145], v170, v[158:159]
	v_min_u32_e32 v144, 1, v144
	v_or_b32_e32 v144, v145, v144
	v_cvt_f32_u32_e32 v144, v144
	v_sub_u32_e32 v145, 32, v170
	v_ldexp_f32 v145, v144, v145
	v_ffbh_u32_e32 v144, v157
	v_min_u32_e32 v144, 32, v144
	v_lshlrev_b64 v[156:157], v144, v[156:157]
	v_min_u32_e32 v156, 1, v156
	v_or_b32_e32 v156, v157, v156
	v_cvt_f32_u32_e32 v156, v156
	v_sub_u32_e32 v144, 32, v144
	v_ldexp_f32 v144, v156, v144
	v_pk_mul_f32 v[144:145], v[144:145], s[6:7] op_sel_hi:[1,0]
	s_nop 0
	v_pk_fma_f32 v[144:145], v[144:145], s[22:23], v[176:177] op_sel_hi:[1,0,0]
	s_nop 0
	v_mul_f32_e32 v156, 0x4b800000, v144
	v_cmp_gt_f32_e64 s[42:43], s0, v144
	v_cmp_gt_f32_e32 vcc, s0, v145
	s_nop 0
	v_cndmask_b32_e64 v144, v144, v156, s[42:43]
	v_mul_f32_e32 v156, 0x4b800000, v145
	v_cndmask_b32_e32 v145, v145, v156, vcc
	v_rsq_f32_e32 v144, v144
	v_rsq_f32_e32 v145, v145
	s_nop 0
	v_pk_mul_f32 v[156:157], v[144:145], s[24:25] op_sel_hi:[1,0]
	s_nop 0
	v_cndmask_b32_e64 v156, v144, v156, s[42:43]
	v_ffbh_u32_e32 v144, v141
	v_min_u32_e32 v144, 32, v144
	v_lshlrev_b64 v[140:141], v144, v[140:141]
	v_min_u32_e32 v140, 1, v140
	v_or_b32_e32 v140, v141, v140
	v_cvt_f32_u32_e32 v140, v140
	v_sub_u32_e32 v141, 32, v144
	v_cndmask_b32_e32 v157, v145, v157, vcc
	v_pk_mul_f32 v[126:127], v[126:127], v[156:157]
	v_ldexp_f32 v141, v140, v141
	v_ffbh_u32_e32 v140, v139
	v_min_u32_e32 v140, 32, v140
	v_lshlrev_b64 v[138:139], v140, v[138:139]
	v_min_u32_e32 v138, 1, v138
	v_or_b32_e32 v138, v139, v138
	v_cvt_f32_u32_e32 v138, v138
	v_sub_u32_e32 v139, 32, v140
	v_pk_mul_f32 v[114:115], v[114:115], v[156:157]
	v_pk_mul_f32 v[98:99], v[98:99], v[156:157]
	v_ldexp_f32 v140, v138, v139
	v_pk_mul_f32 v[138:139], v[140:141], s[6:7] op_sel_hi:[1,0]
	v_pk_mul_f32 v[82:83], v[82:83], v[156:157]
	v_pk_fma_f32 v[138:139], v[138:139], s[22:23], v[176:177] op_sel_hi:[1,0,0]
	v_pk_mul_f32 v[62:63], v[62:63], v[156:157]
	v_mul_f32_e32 v140, 0x4b800000, v138
	v_cmp_gt_f32_e64 s[42:43], s0, v138
	v_cmp_gt_f32_e32 vcc, s0, v139
	v_pk_mul_f32 v[50:51], v[50:51], v[156:157]
	v_cndmask_b32_e64 v138, v138, v140, s[42:43]
	v_mul_f32_e32 v140, 0x4b800000, v139
	v_cndmask_b32_e32 v139, v139, v140, vcc
	v_rsq_f32_e32 v138, v138
	v_rsq_f32_e32 v139, v139
	v_pk_mul_f32 v[34:35], v[34:35], v[156:157]
	v_pk_mul_f32 v[18:19], v[18:19], v[156:157]
	v_pk_mul_f32 v[140:141], v[138:139], s[24:25] op_sel_hi:[1,0]
	s_nop 0
	v_cndmask_b32_e64 v158, v138, v140, s[42:43]
	v_ffbh_u32_e32 v138, v137
	v_min_u32_e32 v138, 32, v138
	v_lshlrev_b64 v[136:137], v138, v[136:137]
	v_min_u32_e32 v136, 1, v136
	v_or_b32_e32 v136, v137, v136
	v_cvt_f32_u32_e32 v136, v136
	v_sub_u32_e32 v137, 32, v138
	v_cndmask_b32_e32 v159, v139, v141, vcc
	v_pk_mul_f32 v[128:129], v[128:129], v[158:159]
	v_ldexp_f32 v137, v136, v137
	v_ffbh_u32_e32 v136, v135
	v_min_u32_e32 v136, 32, v136
	v_lshlrev_b64 v[134:135], v136, v[134:135]
	v_min_u32_e32 v134, 1, v134
	v_or_b32_e32 v134, v135, v134
	v_cvt_f32_u32_e32 v134, v134
	v_sub_u32_e32 v135, 32, v136
	v_pk_mul_f32 v[64:65], v[64:65], v[158:159]
	v_ldexp_f32 v136, v134, v135
	v_pk_mul_f32 v[134:135], v[136:137], s[6:7] op_sel_hi:[1,0]
	s_nop 0
	v_pk_fma_f32 v[134:135], v[134:135], s[22:23], v[176:177] op_sel_hi:[1,0,0]
	s_nop 0
	v_mul_f32_e32 v136, 0x4b800000, v134
	v_cmp_gt_f32_e64 s[42:43], s0, v134
	v_cmp_gt_f32_e32 vcc, s0, v135
	s_nop 0
	v_cndmask_b32_e64 v134, v134, v136, s[42:43]
	v_mul_f32_e32 v136, 0x4b800000, v135
	v_cndmask_b32_e32 v135, v135, v136, vcc
	v_rsq_f32_e32 v134, v134
	v_rsq_f32_e32 v135, v135
	s_nop 0
	v_pk_mul_f32 v[136:137], v[134:135], s[24:25] op_sel_hi:[1,0]
	s_nop 0
	v_cndmask_b32_e64 v170, v134, v136, s[42:43]
	v_ffbh_u32_e32 v134, v133
	v_min_u32_e32 v134, 32, v134
	v_lshlrev_b64 v[132:133], v134, v[132:133]
	v_min_u32_e32 v132, 1, v132
	v_or_b32_e32 v132, v133, v132
	v_cvt_f32_u32_e32 v132, v132
	v_sub_u32_e32 v133, 32, v134
	v_cndmask_b32_e32 v171, v135, v137, vcc
	v_ldexp_f32 v133, v132, v133
	v_ffbh_u32_e32 v132, v131
	v_min_u32_e32 v132, 32, v132
	v_lshlrev_b64 v[130:131], v132, v[130:131]
	v_min_u32_e32 v130, 1, v130
	v_or_b32_e32 v130, v131, v130
	v_cvt_f32_u32_e32 v130, v130
	v_sub_u32_e32 v131, 32, v132
	v_ldexp_f32 v132, v130, v131
	v_pk_mul_f32 v[130:131], v[132:133], s[6:7] op_sel_hi:[1,0]
	s_nop 0
	v_pk_fma_f32 v[130:131], v[130:131], s[22:23], v[176:177] op_sel_hi:[1,0,0]
	s_nop 0
	v_mul_f32_e32 v132, 0x4b800000, v130
	v_cmp_gt_f32_e64 s[42:43], s0, v130
	v_cmp_gt_f32_e32 vcc, s0, v131
	s_nop 0
	v_cndmask_b32_e64 v130, v130, v132, s[42:43]
	v_mul_f32_e32 v132, 0x4b800000, v131
	v_cndmask_b32_e32 v131, v131, v132, vcc
	v_rsq_f32_e32 v130, v130
	v_rsq_f32_e32 v131, v131
	s_nop 0
	v_pk_mul_f32 v[132:133], v[130:131], s[24:25] op_sel_hi:[1,0]
	s_nop 0
	v_cndmask_b32_e32 v173, v131, v133, vcc
	v_cndmask_b32_e64 v172, v130, v132, s[42:43]
	global_load_dwordx4 v[130:133], v[142:143], off offset:1072
	global_load_dwordx4 v[134:137], v[142:143], off offset:1056
	global_load_dwordx4 v[138:141], v[142:143], off offset:1040
	s_nop 0
	global_load_dwordx4 v[142:145], v[142:143], off offset:1024
	s_waitcnt vmcnt(0)
	v_ffbh_u32_e32 v182, v145
	v_min_u32_e32 v182, 32, v182
	v_lshlrev_b64 v[144:145], v182, v[144:145]
	v_min_u32_e32 v144, 1, v144
	v_or_b32_e32 v144, v145, v144
	v_cvt_f32_u32_e32 v144, v144
	v_sub_u32_e32 v145, 32, v182
	v_ldexp_f32 v145, v144, v145
	v_ffbh_u32_e32 v144, v143
	v_min_u32_e32 v144, 32, v144
	v_lshlrev_b64 v[142:143], v144, v[142:143]
	v_min_u32_e32 v142, 1, v142
	v_or_b32_e32 v142, v143, v142
	v_cvt_f32_u32_e32 v142, v142
	v_sub_u32_e32 v143, 32, v144
	v_ldexp_f32 v144, v142, v143
	v_pk_mul_f32 v[142:143], v[144:145], s[6:7] op_sel_hi:[1,0]
	s_nop 0
	v_pk_fma_f32 v[142:143], v[142:143], s[22:23], v[176:177] op_sel_hi:[1,0,0]
	s_nop 0
	v_mul_f32_e32 v144, 0x4b800000, v142
	v_cmp_gt_f32_e64 s[42:43], s0, v142
	v_cmp_gt_f32_e32 vcc, s0, v143
	s_nop 0
	v_cndmask_b32_e64 v142, v142, v144, s[42:43]
	v_mul_f32_e32 v144, 0x4b800000, v143
	v_cndmask_b32_e32 v143, v143, v144, vcc
	v_rsq_f32_e32 v142, v142
	v_rsq_f32_e32 v143, v143
	s_nop 0
	v_pk_mul_f32 v[144:145], v[142:143], s[24:25] op_sel_hi:[1,0]
	s_nop 0
	v_cndmask_b32_e64 v142, v142, v144, s[42:43]
	v_ffbh_u32_e32 v144, v141
	v_min_u32_e32 v144, 32, v144
	v_lshlrev_b64 v[140:141], v144, v[140:141]
	v_min_u32_e32 v140, 1, v140
	v_or_b32_e32 v140, v141, v140
	v_cvt_f32_u32_e32 v140, v140
	v_sub_u32_e32 v141, 32, v144
	v_cndmask_b32_e32 v143, v143, v145, vcc
	v_pk_mul_f32 v[144:145], v[124:125], v[172:173]
	v_ldexp_f32 v141, v140, v141
	v_ffbh_u32_e32 v140, v139
	v_min_u32_e32 v140, 32, v140
	v_lshlrev_b64 v[138:139], v140, v[138:139]
	v_min_u32_e32 v138, 1, v138
	v_or_b32_e32 v138, v139, v138
	v_cvt_f32_u32_e32 v138, v138
	v_sub_u32_e32 v139, 32, v140
	v_pk_mul_f32 v[124:125], v[122:123], v[170:171]
	v_cvt_pk_bf16_f32 v122, v126, v127
	v_ldexp_f32 v140, v138, v139
	v_pk_mul_f32 v[138:139], v[140:141], s[6:7] op_sel_hi:[1,0]
	v_cvt_pk_bf16_f32 v123, v128, v129
	v_cvt_pk_bf16_f32 v124, v124, v125
	v_cvt_pk_bf16_f32 v125, v144, v145
	v_pk_mul_f32 v[118:119], v[118:119], v[142:143]
	v_pk_fma_f32 v[138:139], v[138:139], s[22:23], v[176:177] op_sel_hi:[1,0,0]
	v_pk_mul_f32 v[102:103], v[102:103], v[142:143]
	v_mul_f32_e32 v140, 0x4b800000, v138
	v_cmp_gt_f32_e64 s[42:43], s0, v138
	v_cmp_gt_f32_e32 vcc, s0, v139
	v_pk_mul_f32 v[86:87], v[86:87], v[142:143]
	v_cndmask_b32_e64 v138, v138, v140, s[42:43]
	v_mul_f32_e32 v140, 0x4b800000, v139
	v_cndmask_b32_e32 v139, v139, v140, vcc
	v_rsq_f32_e32 v138, v138
	v_rsq_f32_e32 v139, v139
	v_pk_mul_f32 v[70:71], v[70:71], v[142:143]
	v_pk_mul_f32 v[54:55], v[54:55], v[142:143]
	v_pk_mul_f32 v[38:39], v[38:39], v[142:143]
	v_pk_mul_f32 v[140:141], v[138:139], s[24:25] op_sel_hi:[1,0]
	v_pk_mul_f32 v[22:23], v[22:23], v[142:143]
	v_cndmask_b32_e64 v138, v138, v140, s[42:43]
	v_ffbh_u32_e32 v140, v137
	v_min_u32_e32 v140, 32, v140
	v_lshlrev_b64 v[136:137], v140, v[136:137]
	v_min_u32_e32 v136, 1, v136
	v_or_b32_e32 v136, v137, v136
	v_cvt_f32_u32_e32 v136, v136
	v_sub_u32_e32 v137, 32, v140
	v_cndmask_b32_e32 v139, v139, v141, vcc
	v_lshlrev_b64 v[140:141], 1, v[174:175]
	v_ldexp_f32 v137, v136, v137
	v_ffbh_u32_e32 v136, v135
	v_min_u32_e32 v136, 32, v136
	v_lshlrev_b64 v[134:135], v136, v[134:135]
	v_min_u32_e32 v134, 1, v134
	v_or_b32_e32 v134, v135, v134
	v_cvt_f32_u32_e32 v134, v134
	v_sub_u32_e32 v135, 32, v136
	v_pk_mul_f32 v[120:121], v[120:121], v[138:139]
	v_pk_mul_f32 v[104:105], v[104:105], v[138:139]
	v_ldexp_f32 v136, v134, v135
	v_pk_mul_f32 v[134:135], v[136:137], s[6:7] op_sel_hi:[1,0]
	v_pk_mul_f32 v[88:89], v[88:89], v[138:139]
	v_pk_fma_f32 v[134:135], v[134:135], s[22:23], v[176:177] op_sel_hi:[1,0,0]
	v_pk_mul_f32 v[72:73], v[72:73], v[138:139]
	v_mul_f32_e32 v136, 0x4b800000, v134
	v_cmp_gt_f32_e64 s[42:43], s0, v134
	v_cmp_gt_f32_e32 vcc, s0, v135
	v_pk_mul_f32 v[56:57], v[56:57], v[138:139]
	v_cndmask_b32_e64 v134, v134, v136, s[42:43]
	v_mul_f32_e32 v136, 0x4b800000, v135
	v_cndmask_b32_e32 v135, v135, v136, vcc
	v_rsq_f32_e32 v134, v134
	v_rsq_f32_e32 v135, v135
	v_pk_mul_f32 v[40:41], v[40:41], v[138:139]
	v_pk_mul_f32 v[24:25], v[24:25], v[138:139]
	v_pk_mul_f32 v[8:9], v[8:9], v[138:139]
	v_pk_mul_f32 v[136:137], v[134:135], s[24:25] op_sel_hi:[1,0]
	v_pk_mul_f32 v[6:7], v[6:7], v[142:143]
	v_cndmask_b32_e64 v134, v134, v136, s[42:43]
	v_ffbh_u32_e32 v136, v133
	v_min_u32_e32 v136, 32, v136
	v_lshlrev_b64 v[132:133], v136, v[132:133]
	v_min_u32_e32 v132, 1, v132
	v_or_b32_e32 v132, v133, v132
	v_cvt_f32_u32_e32 v132, v132
	v_sub_u32_e32 v133, 32, v136
	v_cndmask_b32_e32 v135, v135, v137, vcc
	v_lshl_add_u32 v136, s54, 8, v178
	v_ldexp_f32 v133, v132, v133
	v_ffbh_u32_e32 v132, v131
	v_min_u32_e32 v132, 32, v132
	v_lshlrev_b64 v[130:131], v132, v[130:131]
	v_min_u32_e32 v130, 1, v130
	v_or_b32_e32 v130, v131, v130
	v_cvt_f32_u32_e32 v130, v130
	v_sub_u32_e32 v131, 32, v132
	v_ashrrev_i32_e32 v137, 31, v136
	v_ldexp_f32 v132, v130, v131
	v_pk_mul_f32 v[130:131], v[132:133], s[6:7] op_sel_hi:[1,0]
	s_nop 0
	v_pk_fma_f32 v[130:131], v[130:131], s[22:23], v[176:177] op_sel_hi:[1,0,0]
	s_mov_b32 s23, 0xb000
	v_mul_f32_e32 v132, 0x4b800000, v130
	v_cmp_gt_f32_e64 s[42:43], s0, v130
	v_cmp_gt_f32_e32 vcc, s0, v131
	s_mov_b64 s[0:1], 0x400000
	v_cndmask_b32_e64 v130, v130, v132, s[42:43]
	v_mul_f32_e32 v132, 0x4b800000, v131
	v_cndmask_b32_e32 v131, v131, v132, vcc
	v_rsq_f32_e32 v130, v130
	v_rsq_f32_e32 v131, v131
	s_nop 0
	v_pk_mul_f32 v[132:133], v[130:131], s[24:25] op_sel_hi:[1,0]
	s_nop 0
	v_cndmask_b32_e32 v131, v131, v133, vcc
	v_cndmask_b32_e64 v130, v130, v132, s[42:43]
	v_lshlrev_b64 v[132:133], 15, v[136:137]
	v_lshl_add_u64 v[132:133], s[30:31], 0, v[132:133]
	v_lshl_add_u64 v[132:133], v[132:133], 0, v[140:141]
	global_store_dwordx4 v[132:133], v[122:125], off sc1
	s_nop 1
	v_pk_mul_f32 v[122:123], v[112:113], v[130:131]
	v_pk_mul_f32 v[112:113], v[110:111], v[134:135]
	v_cvt_pk_bf16_f32 v110, v118, v119
	v_cvt_pk_bf16_f32 v111, v120, v121
	s_nop 0
	v_cvt_pk_bf16_f32 v112, v112, v113
	v_cvt_pk_bf16_f32 v113, v122, v123
	global_store_dwordx4 v[132:133], v[110:113], off offset:256 sc1
	s_nop 1
	v_or_b32_e32 v110, 16, v136
	v_ashrrev_i32_e32 v111, 31, v110
	v_lshlrev_b64 v[110:111], 15, v[110:111]
	v_lshl_add_u64 v[110:111], s[30:31], 0, v[110:111]
	v_lshl_add_u64 v[110:111], v[110:111], 0, v[140:141]
	v_pk_mul_f32 v[112:113], v[116:117], v[158:159]
	v_pk_mul_f32 v[116:117], v[108:109], v[172:173]
	v_pk_mul_f32 v[108:109], v[106:107], v[170:171]
	v_cvt_pk_bf16_f32 v106, v114, v115
	v_cvt_pk_bf16_f32 v107, v112, v113
	s_nop 0
	v_cvt_pk_bf16_f32 v108, v108, v109
	v_cvt_pk_bf16_f32 v109, v116, v117
	global_store_dwordx4 v[110:111], v[106:109], off sc1
	s_nop 1
	v_pk_mul_f32 v[106:107], v[96:97], v[130:131]
	v_pk_mul_f32 v[96:97], v[94:95], v[134:135]
	v_cvt_pk_bf16_f32 v94, v102, v103
	v_cvt_pk_bf16_f32 v95, v104, v105
	s_nop 0
	v_cvt_pk_bf16_f32 v96, v96, v97
	v_cvt_pk_bf16_f32 v97, v106, v107
	global_store_dwordx4 v[110:111], v[94:97], off offset:256 sc1
	s_nop 1
	v_or_b32_e32 v94, 32, v136
	v_ashrrev_i32_e32 v95, 31, v94
	v_lshlrev_b64 v[94:95], 15, v[94:95]
	v_lshl_add_u64 v[94:95], s[30:31], 0, v[94:95]
	v_lshl_add_u64 v[94:95], v[94:95], 0, v[140:141]
	v_pk_mul_f32 v[96:97], v[100:101], v[158:159]
	v_pk_mul_f32 v[100:101], v[92:93], v[172:173]
	v_pk_mul_f32 v[92:93], v[90:91], v[170:171]
	v_cvt_pk_bf16_f32 v90, v98, v99
	v_cvt_pk_bf16_f32 v91, v96, v97
	s_nop 0
	v_cvt_pk_bf16_f32 v92, v92, v93
	v_cvt_pk_bf16_f32 v93, v100, v101
	global_store_dwordx4 v[94:95], v[90:93], off sc1
	s_nop 1
	v_pk_mul_f32 v[90:91], v[80:81], v[130:131]
	v_pk_mul_f32 v[80:81], v[78:79], v[134:135]
	v_cvt_pk_bf16_f32 v78, v86, v87
	v_cvt_pk_bf16_f32 v79, v88, v89
	s_nop 0
	v_cvt_pk_bf16_f32 v80, v80, v81
	v_cvt_pk_bf16_f32 v81, v90, v91
	global_store_dwordx4 v[94:95], v[78:81], off offset:256 sc1
	s_nop 1
	v_or_b32_e32 v78, 48, v136
	v_ashrrev_i32_e32 v79, 31, v78
	v_lshlrev_b64 v[78:79], 15, v[78:79]
	v_lshl_add_u64 v[78:79], s[30:31], 0, v[78:79]
	v_lshl_add_u64 v[78:79], v[78:79], 0, v[140:141]
	v_pk_mul_f32 v[80:81], v[84:85], v[158:159]
	v_pk_mul_f32 v[84:85], v[76:77], v[172:173]
	v_pk_mul_f32 v[76:77], v[74:75], v[170:171]
	v_cvt_pk_bf16_f32 v74, v82, v83
	v_cvt_pk_bf16_f32 v75, v80, v81
	s_nop 0
	v_cvt_pk_bf16_f32 v76, v76, v77
	v_cvt_pk_bf16_f32 v77, v84, v85
	global_store_dwordx4 v[78:79], v[74:77], off sc1
	s_nop 1
	v_pk_mul_f32 v[74:75], v[68:69], v[130:131]
	v_pk_mul_f32 v[68:69], v[66:67], v[134:135]
	v_cvt_pk_bf16_f32 v66, v70, v71
	v_cvt_pk_bf16_f32 v67, v72, v73
	s_nop 0
	v_cvt_pk_bf16_f32 v68, v68, v69
	v_cvt_pk_bf16_f32 v69, v74, v75
	global_store_dwordx4 v[78:79], v[66:69], off offset:256 sc1
	s_nop 1
	v_lshl_add_u64 v[66:67], v[132:133], 0, s[0:1]
	s_mov_b32 s0, 0x400000
	v_pk_mul_f32 v[68:69], v[60:61], v[172:173]
	v_pk_mul_f32 v[60:61], v[58:59], v[170:171]
	v_cvt_pk_bf16_f32 v58, v62, v63
	v_add_co_u32_e32 v62, vcc, s0, v132
	v_cvt_pk_bf16_f32 v59, v64, v65
	v_cvt_pk_bf16_f32 v60, v60, v61
	v_cvt_pk_bf16_f32 v61, v68, v69
	s_mov_b64 s[0:1], 0x480000
	s_nop 0
	v_addc_co_u32_e32 v63, vcc, 0, v133, vcc
	global_store_dwordx4 v[62:63], v[58:61], off sc1
	s_nop 1
	v_pk_mul_f32 v[58:59], v[48:49], v[130:131]
	v_pk_mul_f32 v[48:49], v[46:47], v[134:135]
	v_cvt_pk_bf16_f32 v46, v54, v55
	v_cvt_pk_bf16_f32 v47, v56, v57
	s_nop 0
	v_cvt_pk_bf16_f32 v48, v48, v49
	v_cvt_pk_bf16_f32 v49, v58, v59
	global_store_dwordx4 v[66:67], v[46:49], off offset:256 sc1
	s_nop 1
	v_lshl_add_u64 v[46:47], v[132:133], 0, s[0:1]
	v_pk_mul_f32 v[48:49], v[52:53], v[158:159]
	s_mov_b32 s0, 0x480000
	v_pk_mul_f32 v[52:53], v[44:45], v[172:173]
	v_pk_mul_f32 v[44:45], v[42:43], v[170:171]
	v_cvt_pk_bf16_f32 v43, v48, v49
	v_add_co_u32_e32 v48, vcc, s0, v132
	v_cvt_pk_bf16_f32 v42, v50, v51
	v_cvt_pk_bf16_f32 v44, v44, v45
	v_cvt_pk_bf16_f32 v45, v52, v53
	s_mov_b64 s[0:1], 0x500000
	s_nop 0
	v_addc_co_u32_e32 v49, vcc, 0, v133, vcc
	global_store_dwordx4 v[48:49], v[42:45], off sc1
	s_nop 1
	v_pk_mul_f32 v[42:43], v[32:33], v[130:131]
	v_pk_mul_f32 v[32:33], v[30:31], v[134:135]
	v_cvt_pk_bf16_f32 v30, v38, v39
	v_cvt_pk_bf16_f32 v31, v40, v41
	s_nop 0
	v_cvt_pk_bf16_f32 v32, v32, v33
	v_cvt_pk_bf16_f32 v33, v42, v43
	global_store_dwordx4 v[46:47], v[30:33], off offset:256 sc1
	s_nop 1
	v_lshl_add_u64 v[30:31], v[132:133], 0, s[0:1]
	v_pk_mul_f32 v[32:33], v[36:37], v[158:159]
	s_mov_b32 s0, 0x500000
	v_pk_mul_f32 v[36:37], v[28:29], v[172:173]
	v_pk_mul_f32 v[28:29], v[26:27], v[170:171]
	v_cvt_pk_bf16_f32 v27, v32, v33
	v_add_co_u32_e32 v32, vcc, s0, v132
	v_cvt_pk_bf16_f32 v26, v34, v35
	v_cvt_pk_bf16_f32 v28, v28, v29
	v_cvt_pk_bf16_f32 v29, v36, v37
	s_mov_b64 s[0:1], 0x580000
	s_nop 0
	v_addc_co_u32_e32 v33, vcc, 0, v133, vcc
	global_store_dwordx4 v[32:33], v[26:29], off sc1
	s_nop 1
	v_pk_mul_f32 v[26:27], v[16:17], v[130:131]
	v_pk_mul_f32 v[16:17], v[14:15], v[134:135]
	v_cvt_pk_bf16_f32 v14, v22, v23
	v_cvt_pk_bf16_f32 v15, v24, v25
	s_nop 0
	v_cvt_pk_bf16_f32 v16, v16, v17
	v_cvt_pk_bf16_f32 v17, v26, v27
	global_store_dwordx4 v[30:31], v[14:17], off offset:256 sc1
	s_nop 1
	v_lshl_add_u64 v[14:15], v[132:133], 0, s[0:1]
	v_pk_mul_f32 v[16:17], v[20:21], v[158:159]
	s_mov_b32 s0, 0x580000
	v_pk_mul_f32 v[20:21], v[12:13], v[172:173]
	v_pk_mul_f32 v[12:13], v[10:11], v[170:171]
	v_cvt_pk_bf16_f32 v11, v16, v17
	v_add_co_u32_e32 v16, vcc, s0, v132
	v_cvt_pk_bf16_f32 v10, v18, v19
	v_cvt_pk_bf16_f32 v12, v12, v13
	v_cvt_pk_bf16_f32 v13, v20, v21
	s_mov_b64 s[0:1], -1
	s_nop 0
	v_addc_co_u32_e32 v17, vcc, 0, v133, vcc
	global_store_dwordx4 v[16:17], v[10:13], off sc1
	s_andn2_b64 vcc, exec, s[40:41]
	s_nop 0
	v_pk_mul_f32 v[10:11], v[4:5], v[130:131]
	v_pk_mul_f32 v[4:5], v[2:3], v[134:135]
	v_cvt_pk_bf16_f32 v2, v6, v7
	v_cvt_pk_bf16_f32 v3, v8, v9
	s_nop 0
	v_cvt_pk_bf16_f32 v4, v4, v5
	v_cvt_pk_bf16_f32 v5, v10, v11
	global_store_dwordx4 v[14:15], v[2:5], off offset:256 sc1
	s_cbranch_vccnz .LBB0_774
	s_andn2_b64 vcc, exec, s[26:27]
	s_cbranch_vccnz .LBB0_773
	s_barrier
	s_branch .LBB0_773
